# v3: all cache-copy units (incl. S5 share) spread over 11 idle GEMM slots; S5 passes carry no copy; FFN1in-L1 uses reversed block order behind KV
# speedup vs baseline: 1.0344x; 1.0080x over previous
.LBB0_201:
	s_cmp_lt_u32 s33, 1200
	s_cbranch_scc1 .Lcpya_end
	v_lshrrev_b32_e32 v21, 6, v174
	v_and_b32_e32 v22, 63, v174
	v_lshlrev_b32_e32 v22, 4, v22
	v_readfirstlane_b32 s80, v21
	v_add_u32_e32 v23, 0x1000, v22
	v_readfirstlane_b32 s92, v235
	v_readfirstlane_b32 s93, v236
	v_readfirstlane_b32 s94, v237
	v_readfirstlane_b32 s95, v238
	v_readfirstlane_b32 s98, v239
	v_readfirstlane_b32 s99, v240
	s_add_i32 s80, s80, s33
	s_add_i32 s80, s80, 0xfffffb50
	s_sub_i32 s100, s78, 150
	s_lshl_b32 s100, s100, 3
.Lcpya_loop:
	s_add_i32 s101, s80, s100
	s_cmp_lt_u32 s101, 0xfa0
	s_cbranch_scc0 .Lcpya_tail
	s_mul_hi_u32 s81, s80, 0x2ad5802b
	s_lshr_b32 s81, s81, 8
	s_mul_i32 s82, s81, 0x5fa
	s_sub_i32 s82, s80, s82
	s_lshl_b32 s82, s82, 13
	s_and_b32 s83, s81, 31
	s_mul_i32 s83, s83, 0xc00000
	s_add_i32 s82, s82, s83
	s_cmp_lt_u32 s81, 32
	s_cselect_b32 s84, s92, s94
	s_cselect_b32 s85, s93, s95
	s_mov_b32 s83, 0x1f210000
	s_cselect_b32 s83, 0x7210000, s83
	s_add_u32 s84, s84, s82
	s_addc_u32 s85, s85, 0
	s_add_u32 s84, s84, 0xc000
	s_addc_u32 s85, s85, 0
	s_add_u32 s83, s83, s82
	s_add_u32 s86, s98, s83
	s_addc_u32 s87, s99, 0
	s_mul_hi_u32 s81, s101, 0x2ad5802b
	s_lshr_b32 s81, s81, 8
	s_mul_i32 s82, s81, 0x5fa
	s_sub_i32 s82, s101, s82
	s_lshl_b32 s82, s82, 13
	s_and_b32 s83, s81, 31
	s_mul_i32 s83, s83, 0xc00000
	s_add_i32 s82, s82, s83
	s_cmp_lt_u32 s81, 32
	s_cselect_b32 s88, s92, s94
	s_cselect_b32 s89, s93, s95
	s_mov_b32 s83, 0x1f210000
	s_cselect_b32 s83, 0x7210000, s83
	s_add_u32 s88, s88, s82
	s_addc_u32 s89, s89, 0
	s_add_u32 s88, s88, 0xc000
	s_addc_u32 s89, s89, 0
	s_add_u32 s83, s83, s82
	s_add_u32 s90, s98, s83
	s_addc_u32 s91, s99, 0
	global_load_dwordx4 v[64:67], v22, s[84:85] nt
	global_load_dwordx4 v[68:71], v22, s[84:85] offset:1024 nt
	global_load_dwordx4 v[72:75], v22, s[84:85] offset:2048 nt
	global_load_dwordx4 v[76:79], v22, s[84:85] offset:3072 nt
	global_load_dwordx4 v[80:83], v23, s[84:85] nt
	global_load_dwordx4 v[84:87], v23, s[84:85] offset:1024 nt
	global_load_dwordx4 v[88:91], v23, s[84:85] offset:2048 nt
	global_load_dwordx4 v[92:95], v23, s[84:85] offset:3072 nt
	global_load_dwordx4 v[96:99], v22, s[88:89] nt
	global_load_dwordx4 v[100:103], v22, s[88:89] offset:1024 nt
	global_load_dwordx4 v[104:107], v22, s[88:89] offset:2048 nt
	global_load_dwordx4 v[108:111], v22, s[88:89] offset:3072 nt
	global_load_dwordx4 v[112:115], v23, s[88:89] nt
	global_load_dwordx4 v[116:119], v23, s[88:89] offset:1024 nt
	global_load_dwordx4 v[120:123], v23, s[88:89] offset:2048 nt
	global_load_dwordx4 v[124:127], v23, s[88:89] offset:3072 nt
	s_waitcnt vmcnt(15)
	global_store_dwordx4 v22, v[64:67], s[86:87] nt
	s_waitcnt vmcnt(15)
	global_store_dwordx4 v22, v[68:71], s[86:87] offset:1024 nt
	s_waitcnt vmcnt(15)
	global_store_dwordx4 v22, v[72:75], s[86:87] offset:2048 nt
	s_waitcnt vmcnt(15)
	global_store_dwordx4 v22, v[76:79], s[86:87] offset:3072 nt
	s_waitcnt vmcnt(15)
	global_store_dwordx4 v23, v[80:83], s[86:87] nt
	s_waitcnt vmcnt(15)
	global_store_dwordx4 v23, v[84:87], s[86:87] offset:1024 nt
	s_waitcnt vmcnt(15)
	global_store_dwordx4 v23, v[88:91], s[86:87] offset:2048 nt
	s_waitcnt vmcnt(15)
	global_store_dwordx4 v23, v[92:95], s[86:87] offset:3072 nt
	s_waitcnt vmcnt(15)
	global_store_dwordx4 v22, v[96:99], s[90:91] nt
	s_waitcnt vmcnt(15)
	global_store_dwordx4 v22, v[100:103], s[90:91] offset:1024 nt
	s_waitcnt vmcnt(15)
	global_store_dwordx4 v22, v[104:107], s[90:91] offset:2048 nt
	s_waitcnt vmcnt(15)
	global_store_dwordx4 v22, v[108:111], s[90:91] offset:3072 nt
	s_waitcnt vmcnt(15)
	global_store_dwordx4 v23, v[112:115], s[90:91] nt
	s_waitcnt vmcnt(15)
	global_store_dwordx4 v23, v[116:119], s[90:91] offset:1024 nt
	s_waitcnt vmcnt(15)
	global_store_dwordx4 v23, v[120:123], s[90:91] offset:2048 nt
	s_waitcnt vmcnt(15)
	global_store_dwordx4 v23, v[124:127], s[90:91] offset:3072 nt
	s_add_i32 s80, s101, s100
	s_branch .Lcpya_loop
.Lcpya_tail:
	s_cmp_lt_u32 s80, 0xfa0
	s_cbranch_scc0 .Lcpya_end
	s_mul_hi_u32 s81, s80, 0x2ad5802b
	s_lshr_b32 s81, s81, 8
	s_mul_i32 s82, s81, 0x5fa
	s_sub_i32 s82, s80, s82
	s_lshl_b32 s82, s82, 13
	s_and_b32 s83, s81, 31
	s_mul_i32 s83, s83, 0xc00000
	s_add_i32 s82, s82, s83
	s_cmp_lt_u32 s81, 32
	s_cselect_b32 s84, s92, s94
	s_cselect_b32 s85, s93, s95
	s_mov_b32 s83, 0x1f210000
	s_cselect_b32 s83, 0x7210000, s83
	s_add_u32 s84, s84, s82
	s_addc_u32 s85, s85, 0
	s_add_u32 s84, s84, 0xc000
	s_addc_u32 s85, s85, 0
	s_add_u32 s83, s83, s82
	s_add_u32 s86, s98, s83
	s_addc_u32 s87, s99, 0
	global_load_dwordx4 v[64:67], v22, s[84:85] nt
	global_load_dwordx4 v[68:71], v22, s[84:85] offset:1024 nt
	global_load_dwordx4 v[72:75], v22, s[84:85] offset:2048 nt
	global_load_dwordx4 v[76:79], v22, s[84:85] offset:3072 nt
	global_load_dwordx4 v[80:83], v23, s[84:85] nt
	global_load_dwordx4 v[84:87], v23, s[84:85] offset:1024 nt
	global_load_dwordx4 v[88:91], v23, s[84:85] offset:2048 nt
	global_load_dwordx4 v[92:95], v23, s[84:85] offset:3072 nt
	s_waitcnt vmcnt(7)
	global_store_dwordx4 v22, v[64:67], s[86:87] nt
	s_waitcnt vmcnt(7)
	global_store_dwordx4 v22, v[68:71], s[86:87] offset:1024 nt
	s_waitcnt vmcnt(7)
	global_store_dwordx4 v22, v[72:75], s[86:87] offset:2048 nt
	s_waitcnt vmcnt(7)
	global_store_dwordx4 v22, v[76:79], s[86:87] offset:3072 nt
	s_waitcnt vmcnt(7)
	global_store_dwordx4 v23, v[80:83], s[86:87] nt
	s_waitcnt vmcnt(7)
	global_store_dwordx4 v23, v[84:87], s[86:87] offset:1024 nt
	s_waitcnt vmcnt(7)
	global_store_dwordx4 v23, v[88:91], s[86:87] offset:2048 nt
	s_waitcnt vmcnt(7)
	global_store_dwordx4 v23, v[92:95], s[86:87] offset:3072 nt

.LBB0_263:
	s_cmp_lt_u32 s33, 32
	s_cbranch_scc1 .Lcpy1_end
	v_lshrrev_b32_e32 v21, 6, v174
	v_and_b32_e32 v22, 63, v174
	v_lshlrev_b32_e32 v22, 4, v22
	v_readfirstlane_b32 s80, v21
	v_add_u32_e32 v23, 0x1000, v22
	v_readfirstlane_b32 s92, v235
	v_readfirstlane_b32 s93, v236
	v_readfirstlane_b32 s94, v237
	v_readfirstlane_b32 s95, v238
	v_readfirstlane_b32 s98, v239
	v_readfirstlane_b32 s99, v240
	s_add_i32 s80, s80, s33
	s_add_i32 s80, s80, 0xf80
	s_sub_i32 s100, s78, 4
	s_lshl_b32 s100, s100, 3
.Lcpy1_loop:
	s_add_i32 s101, s80, s100
	s_cmp_lt_u32 s101, 0x5208
	s_cbranch_scc0 .Lcpy1_tail
	s_mul_hi_u32 s81, s80, 0x2ad5802b
	s_lshr_b32 s81, s81, 8
	s_mul_i32 s82, s81, 0x5fa
	s_sub_i32 s82, s80, s82
	s_lshl_b32 s82, s82, 13
	s_and_b32 s83, s81, 31
	s_mul_i32 s83, s83, 0xc00000
	s_add_i32 s82, s82, s83
	s_cmp_lt_u32 s81, 32
	s_cselect_b32 s84, s92, s94
	s_cselect_b32 s85, s93, s95
	s_mov_b32 s83, 0x1f210000
	s_cselect_b32 s83, 0x7210000, s83
	s_add_u32 s84, s84, s82
	s_addc_u32 s85, s85, 0
	s_add_u32 s84, s84, 0xc000
	s_addc_u32 s85, s85, 0
	s_add_u32 s83, s83, s82
	s_add_u32 s86, s98, s83
	s_addc_u32 s87, s99, 0
	s_mul_hi_u32 s81, s101, 0x2ad5802b
	s_lshr_b32 s81, s81, 8
	s_mul_i32 s82, s81, 0x5fa
	s_sub_i32 s82, s101, s82
	s_lshl_b32 s82, s82, 13
	s_and_b32 s83, s81, 31
	s_mul_i32 s83, s83, 0xc00000
	s_add_i32 s82, s82, s83
	s_cmp_lt_u32 s81, 32
	s_cselect_b32 s88, s92, s94
	s_cselect_b32 s89, s93, s95
	s_mov_b32 s83, 0x1f210000
	s_cselect_b32 s83, 0x7210000, s83
	s_add_u32 s88, s88, s82
	s_addc_u32 s89, s89, 0
	s_add_u32 s88, s88, 0xc000
	s_addc_u32 s89, s89, 0
	s_add_u32 s83, s83, s82
	s_add_u32 s90, s98, s83
	s_addc_u32 s91, s99, 0
	global_load_dwordx4 v[64:67], v22, s[84:85] nt
	global_load_dwordx4 v[68:71], v22, s[84:85] offset:1024 nt
	global_load_dwordx4 v[72:75], v22, s[84:85] offset:2048 nt
	global_load_dwordx4 v[76:79], v22, s[84:85] offset:3072 nt
	global_load_dwordx4 v[80:83], v23, s[84:85] nt
	global_load_dwordx4 v[84:87], v23, s[84:85] offset:1024 nt
	global_load_dwordx4 v[88:91], v23, s[84:85] offset:2048 nt
	global_load_dwordx4 v[92:95], v23, s[84:85] offset:3072 nt
	global_load_dwordx4 v[96:99], v22, s[88:89] nt
	global_load_dwordx4 v[100:103], v22, s[88:89] offset:1024 nt
	global_load_dwordx4 v[104:107], v22, s[88:89] offset:2048 nt
	global_load_dwordx4 v[108:111], v22, s[88:89] offset:3072 nt
	global_load_dwordx4 v[112:115], v23, s[88:89] nt
	global_load_dwordx4 v[116:119], v23, s[88:89] offset:1024 nt
	global_load_dwordx4 v[120:123], v23, s[88:89] offset:2048 nt
	global_load_dwordx4 v[124:127], v23, s[88:89] offset:3072 nt
	s_waitcnt vmcnt(15)
	global_store_dwordx4 v22, v[64:67], s[86:87] nt
	s_waitcnt vmcnt(15)
	global_store_dwordx4 v22, v[68:71], s[86:87] offset:1024 nt
	s_waitcnt vmcnt(15)
	global_store_dwordx4 v22, v[72:75], s[86:87] offset:2048 nt
	s_waitcnt vmcnt(15)
	global_store_dwordx4 v22, v[76:79], s[86:87] offset:3072 nt
	s_waitcnt vmcnt(15)
	global_store_dwordx4 v23, v[80:83], s[86:87] nt
	s_waitcnt vmcnt(15)
	global_store_dwordx4 v23, v[84:87], s[86:87] offset:1024 nt
	s_waitcnt vmcnt(15)
	global_store_dwordx4 v23, v[88:91], s[86:87] offset:2048 nt
	s_waitcnt vmcnt(15)
	global_store_dwordx4 v23, v[92:95], s[86:87] offset:3072 nt
	s_waitcnt vmcnt(15)
	global_store_dwordx4 v22, v[96:99], s[90:91] nt
	s_waitcnt vmcnt(15)
	global_store_dwordx4 v22, v[100:103], s[90:91] offset:1024 nt
	s_waitcnt vmcnt(15)
	global_store_dwordx4 v22, v[104:107], s[90:91] offset:2048 nt
	s_waitcnt vmcnt(15)
	global_store_dwordx4 v22, v[108:111], s[90:91] offset:3072 nt
	s_waitcnt vmcnt(15)
	global_store_dwordx4 v23, v[112:115], s[90:91] nt
	s_waitcnt vmcnt(15)
	global_store_dwordx4 v23, v[116:119], s[90:91] offset:1024 nt
	s_waitcnt vmcnt(15)
	global_store_dwordx4 v23, v[120:123], s[90:91] offset:2048 nt
	s_waitcnt vmcnt(15)
	global_store_dwordx4 v23, v[124:127], s[90:91] offset:3072 nt
	s_add_i32 s80, s101, s100
	s_branch .Lcpy1_loop
.Lcpy1_tail:
	s_cmp_lt_u32 s80, 0x5208
	s_cbranch_scc0 .Lcpy1_end
	s_mul_hi_u32 s81, s80, 0x2ad5802b
	s_lshr_b32 s81, s81, 8
	s_mul_i32 s82, s81, 0x5fa
	s_sub_i32 s82, s80, s82
	s_lshl_b32 s82, s82, 13
	s_and_b32 s83, s81, 31
	s_mul_i32 s83, s83, 0xc00000
	s_add_i32 s82, s82, s83
	s_cmp_lt_u32 s81, 32
	s_cselect_b32 s84, s92, s94
	s_cselect_b32 s85, s93, s95
	s_mov_b32 s83, 0x1f210000
	s_cselect_b32 s83, 0x7210000, s83
	s_add_u32 s84, s84, s82
	s_addc_u32 s85, s85, 0
	s_add_u32 s84, s84, 0xc000
	s_addc_u32 s85, s85, 0
	s_add_u32 s83, s83, s82
	s_add_u32 s86, s98, s83
	s_addc_u32 s87, s99, 0
	global_load_dwordx4 v[64:67], v22, s[84:85] nt
	global_load_dwordx4 v[68:71], v22, s[84:85] offset:1024 nt
	global_load_dwordx4 v[72:75], v22, s[84:85] offset:2048 nt
	global_load_dwordx4 v[76:79], v22, s[84:85] offset:3072 nt
	global_load_dwordx4 v[80:83], v23, s[84:85] nt
	global_load_dwordx4 v[84:87], v23, s[84:85] offset:1024 nt
	global_load_dwordx4 v[88:91], v23, s[84:85] offset:2048 nt
	global_load_dwordx4 v[92:95], v23, s[84:85] offset:3072 nt
	s_waitcnt vmcnt(7)
	global_store_dwordx4 v22, v[64:67], s[86:87] nt
	s_waitcnt vmcnt(7)
	global_store_dwordx4 v22, v[68:71], s[86:87] offset:1024 nt
	s_waitcnt vmcnt(7)
	global_store_dwordx4 v22, v[72:75], s[86:87] offset:2048 nt
	s_waitcnt vmcnt(7)
	global_store_dwordx4 v22, v[76:79], s[86:87] offset:3072 nt
	s_waitcnt vmcnt(7)
	global_store_dwordx4 v23, v[80:83], s[86:87] nt
	s_waitcnt vmcnt(7)
	global_store_dwordx4 v23, v[84:87], s[86:87] offset:1024 nt
	s_waitcnt vmcnt(7)
	global_store_dwordx4 v23, v[88:91], s[86:87] offset:2048 nt
	s_waitcnt vmcnt(7)
	global_store_dwordx4 v23, v[92:95], s[86:87] offset:3072 nt

.LBB0_285:
	v_lshl_add_u32 v16, s56, 3, v117
	v_mul_hi_i32 v17, v16, s4
	v_lshrrev_b32_e32 v18, 31, v17
	v_ashrrev_i32_e32 v17, 8, v17
	v_add_u32_e32 v17, v17, v18
	v_mul_i32_i24_e32 v18, 0x5fa, v17
	v_and_b32_e32 v19, 31, v17
	v_sub_u32_e32 v18, v16, v18
	v_cmp_gt_u32_e64 s[8:9], 32, v17
	v_mul_u32_u24_e32 v19, 0x300000, v19
	v_lshlrev_b32_e32 v88, 2, v19
	v_cndmask_b32_e64 v17, v120, v121, s[8:9]
	v_cndmask_b32_e64 v16, v122, v123, s[8:9]
	v_mov_b32_e32 v89, v81
	v_lshlrev_b32_e32 v90, 9, v18
	v_lshl_add_u64 v[16:17], v[16:17], 0, v[88:89]
	v_ashrrev_i32_e32 v91, 31, v90
	v_lshl_add_u64 v[16:17], v[90:91], 4, v[16:17]
	v_lshl_add_u64 v[16:17], v[16:17], 0, v[84:85]
	v_add_co_u32_e32 v20, vcc, s5, v16
	v_lshl_add_u64 v[18:19], v[16:17], 0, s[12:13]
	s_nop 0
	v_addc_co_u32_e32 v21, vcc, 0, v17, vcc
	v_add_co_u32_e32 v16, vcc, 0xd000, v16
	v_addc_co_u32_e32 v17, vcc, 0, v17, vcc
	s_ashr_i32 s30, s56, 10
	s_bfe_u32 s62, s56, 0x70003
	s_and_b32 s31, s56, 7
	s_and_saveexec_b64 s[34:35], s[6:7]
	s_cbranch_execz .LBB0_288
	s_lshl_b32 s36, s30, 13
	s_lshl_b32 s37, s62, 6
	s_or_b32 s63, s37, s36
	s_lshl_b32 s52, s31, 9
	s_add_u32 s36, s38, s52
	s_addc_u32 s37, s39, 0
	s_add_u32 s52, s42, s52
	s_addc_u32 s53, s43, 0
	s_mov_b64 s[54:55], 0
	v_mov_b32_e32 v16, v119
	v_mov_b32_e32 v17, v116

.LBB0_298:
	s_or_b32 s34, s31, 0x6000
	v_pk_mul_f32 v[128:129], v[112:113], v[114:115]
	v_add_u32_e32 v80, s34, v118
	s_or_b32 s35, s31, 0x6200
	s_or_b32 s37, s31, 0x6600
	v_pk_fma_f32 v[172:173], v[94:95], v[114:115], v[128:129] op_sel:[0,0,1] op_sel_hi:[1,1,0] neg_lo:[0,0,1] neg_hi:[0,0,1]
	v_pk_fma_f32 v[114:115], v[94:95], v[114:115], v[128:129] op_sel:[0,0,1] op_sel_hi:[1,1,0]
	ds_read_b128 v[128:131], v80
	ds_read_b128 v[132:135], v80 offset:16
	ds_read_b128 v[136:139], v80 offset:32
	ds_read_b128 v[140:143], v80 offset:48
	s_or_b32 s36, s31, 0x6400
	v_add_u32_e32 v83, s35, v118
	v_add_u32_e32 v114, s37, v118
	v_add_u32_e32 v89, s36, v118
	v_mov_b32_e32 v173, v115
	ds_read_b128 v[144:147], v83
	ds_read_b128 v[148:151], v83 offset:16
	ds_read_b128 v[152:155], v83 offset:32
	ds_read_b128 v[156:159], v83 offset:48
	ds_read_b128 v[160:163], v89
	ds_read_b128 v[164:167], v89 offset:16
	ds_read_b128 v[168:171], v89 offset:32
	ds_read_b128 v[178:181], v89 offset:48
	ds_read_b128 v[182:185], v114
	ds_read_b128 v[186:189], v114 offset:16
	ds_read_b128 v[190:193], v114 offset:32
	ds_read_b128 v[194:197], v114 offset:48
	s_waitcnt lgkmcnt(14)
	v_pk_fma_f32 v[114:115], v[16:17], v[128:129], 0 op_sel_hi:[1,0,0]
	v_mov_b32_e32 v80, v131
	v_pk_fma_f32 v[114:115], v[110:111], v[128:129], v[114:115] op_sel:[0,1,0]
	s_waitcnt lgkmcnt(11)
	v_pk_fma_f32 v[204:205], v[16:17], v[144:145], 0 op_sel_hi:[1,0,0]
	v_pk_fma_f32 v[114:115], v[18:19], v[130:131], v[114:115] op_sel_hi:[1,0,1]
	v_pk_fma_f32 v[128:129], v[110:111], v[144:145], v[204:205] op_sel:[0,1,0]
	v_pk_fma_f32 v[114:115], v[108:109], v[80:81], v[114:115] op_sel_hi:[1,0,1]
	v_mov_b32_e32 v198, v135
	v_pk_fma_f32 v[114:115], v[20:21], v[132:133], v[114:115] op_sel_hi:[1,0,1]
	v_mov_b32_e32 v206, v147
	v_pk_fma_f32 v[114:115], v[106:107], v[132:133], v[114:115] op_sel:[0,1,0]
	v_pk_fma_f32 v[128:129], v[18:19], v[146:147], v[128:129] op_sel_hi:[1,0,1]
	v_pk_fma_f32 v[114:115], v[22:23], v[134:135], v[114:115] op_sel_hi:[1,0,1]
	v_pk_fma_f32 v[128:129], v[108:109], v[206:207], v[128:129] op_sel_hi:[1,0,1]
	v_pk_fma_f32 v[114:115], v[104:105], v[198:199], v[114:115] op_sel_hi:[1,0,1]
	s_waitcnt lgkmcnt(7)
	v_pk_fma_f32 v[214:215], v[16:17], v[160:161], 0 op_sel_hi:[1,0,0]
	v_pk_fma_f32 v[128:129], v[20:21], v[148:149], v[128:129] op_sel_hi:[1,0,1]
	v_pk_fma_f32 v[114:115], v[24:25], v[136:137], v[114:115] op_sel_hi:[1,0,1]
	v_pk_fma_f32 v[144:145], v[110:111], v[160:161], v[214:215] op_sel:[0,1,0]
	v_pk_fma_f32 v[128:129], v[106:107], v[148:149], v[128:129] op_sel:[0,1,0]
	v_pk_fma_f32 v[114:115], v[102:103], v[136:137], v[114:115] op_sel:[0,1,0]
	v_mov_b32_e32 v200, v139
	v_mov_b32_e32 v208, v151
	v_mov_b32_e32 v216, v163
	v_pk_fma_f32 v[130:131], v[18:19], v[162:163], v[144:145] op_sel_hi:[1,0,1]
	v_pk_fma_f32 v[128:129], v[22:23], v[150:151], v[128:129] op_sel_hi:[1,0,1]
	v_pk_fma_f32 v[114:115], v[26:27], v[138:139], v[114:115] op_sel_hi:[1,0,1]
	v_pk_fma_f32 v[130:131], v[108:109], v[216:217], v[130:131] op_sel_hi:[1,0,1]
	v_pk_fma_f32 v[128:129], v[104:105], v[208:209], v[128:129] op_sel_hi:[1,0,1]
	v_pk_fma_f32 v[114:115], v[100:101], v[200:201], v[114:115] op_sel_hi:[1,0,1]
	s_waitcnt lgkmcnt(3)
	v_pk_fma_f32 v[224:225], v[16:17], v[182:183], 0 op_sel_hi:[1,0,0]
	v_pk_fma_f32 v[130:131], v[20:21], v[164:165], v[130:131] op_sel_hi:[1,0,1]
	v_pk_fma_f32 v[128:129], v[24:25], v[152:153], v[128:129] op_sel_hi:[1,0,1]
	v_pk_fma_f32 v[114:115], v[28:29], v[140:141], v[114:115] op_sel_hi:[1,0,1]
	v_pk_fma_f32 v[160:161], v[110:111], v[182:183], v[224:225] op_sel:[0,1,0]
	v_pk_fma_f32 v[130:131], v[106:107], v[164:165], v[130:131] op_sel:[0,1,0]
	v_pk_fma_f32 v[128:129], v[102:103], v[152:153], v[128:129] op_sel:[0,1,0]
	v_pk_fma_f32 v[114:115], v[98:99], v[140:141], v[114:115] op_sel:[0,1,0]
	v_mov_b32_e32 v202, v143
	v_mov_b32_e32 v210, v155
	v_mov_b32_e32 v218, v167
	v_mov_b32_e32 v226, v185
	v_pk_fma_f32 v[144:145], v[18:19], v[184:185], v[160:161] op_sel_hi:[1,0,1]
	v_pk_fma_f32 v[130:131], v[22:23], v[166:167], v[130:131] op_sel_hi:[1,0,1]
	v_pk_fma_f32 v[128:129], v[26:27], v[154:155], v[128:129] op_sel_hi:[1,0,1]
	v_pk_fma_f32 v[114:115], v[30:31], v[142:143], v[114:115] op_sel_hi:[1,0,1]
	v_pk_fma_f32 v[144:145], v[108:109], v[226:227], v[144:145] op_sel_hi:[1,0,1]
	v_pk_fma_f32 v[130:131], v[104:105], v[218:219], v[130:131] op_sel_hi:[1,0,1]
	v_pk_fma_f32 v[128:129], v[100:101], v[210:211], v[128:129] op_sel_hi:[1,0,1]
	v_pk_fma_f32 v[114:115], v[96:97], v[202:203], v[114:115] op_sel_hi:[1,0,1]
	s_waitcnt lgkmcnt(2)
	v_pk_fma_f32 v[144:145], v[20:21], v[186:187], v[144:145] op_sel_hi:[1,0,1]
	v_pk_fma_f32 v[130:131], v[24:25], v[168:169], v[130:131] op_sel_hi:[1,0,1]
	v_pk_fma_f32 v[128:129], v[28:29], v[156:157], v[128:129] op_sel_hi:[1,0,1]
	v_pk_add_f32 v[114:115], v[172:173], v[114:115]
	v_pk_fma_f32 v[132:133], v[106:107], v[186:187], v[144:145] op_sel:[0,1,0]
	v_pk_fma_f32 v[130:131], v[102:103], v[168:169], v[130:131] op_sel:[0,1,0]
	v_pk_fma_f32 v[128:129], v[98:99], v[156:157], v[128:129] op_sel:[0,1,0]
	v_pk_mul_f32 v[134:135], v[112:113], v[114:115]
	v_mov_b32_e32 v212, v159
	v_mov_b32_e32 v220, v171
	v_mov_b32_e32 v228, v189
	v_pk_fma_f32 v[132:133], v[22:23], v[188:189], v[132:133] op_sel_hi:[1,0,1]
	v_pk_fma_f32 v[130:131], v[26:27], v[170:171], v[130:131] op_sel_hi:[1,0,1]
	v_pk_fma_f32 v[128:129], v[30:31], v[158:159], v[128:129] op_sel_hi:[1,0,1]
	v_pk_fma_f32 v[136:137], v[94:95], v[114:115], v[134:135] op_sel:[0,0,1] op_sel_hi:[1,1,0] neg_lo:[0,0,1] neg_hi:[0,0,1]
	v_pk_fma_f32 v[114:115], v[94:95], v[114:115], v[134:135] op_sel:[0,0,1] op_sel_hi:[1,1,0]
	v_pk_fma_f32 v[132:133], v[104:105], v[228:229], v[132:133] op_sel_hi:[1,0,1]
	v_pk_fma_f32 v[130:131], v[100:101], v[220:221], v[130:131] op_sel_hi:[1,0,1]
	v_pk_fma_f32 v[128:129], v[96:97], v[212:213], v[128:129] op_sel_hi:[1,0,1]
	v_mov_b32_e32 v137, v115
	s_waitcnt lgkmcnt(1)
	v_pk_fma_f32 v[132:133], v[24:25], v[190:191], v[132:133] op_sel_hi:[1,0,1]
	v_pk_fma_f32 v[130:131], v[28:29], v[178:179], v[130:131] op_sel_hi:[1,0,1]
	v_pk_add_f32 v[114:115], v[136:137], v[128:129]
	v_pk_fma_f32 v[132:133], v[102:103], v[190:191], v[132:133] op_sel:[0,1,0]
	v_pk_fma_f32 v[130:131], v[98:99], v[178:179], v[130:131] op_sel:[0,1,0]
	v_pk_mul_f32 v[128:129], v[112:113], v[114:115]
	v_mov_b32_e32 v222, v181
	v_mov_b32_e32 v230, v193
	v_pk_fma_f32 v[132:133], v[26:27], v[192:193], v[132:133] op_sel_hi:[1,0,1]
	v_pk_fma_f32 v[130:131], v[30:31], v[180:181], v[130:131] op_sel_hi:[1,0,1]
	v_pk_fma_f32 v[134:135], v[94:95], v[114:115], v[128:129] op_sel:[0,0,1] op_sel_hi:[1,1,0] neg_lo:[0,0,1] neg_hi:[0,0,1]
	v_pk_fma_f32 v[114:115], v[94:95], v[114:115], v[128:129] op_sel:[0,0,1] op_sel_hi:[1,1,0]
	v_pk_fma_f32 v[132:133], v[100:101], v[230:231], v[132:133] op_sel_hi:[1,0,1]
	v_pk_fma_f32 v[130:131], v[96:97], v[222:223], v[130:131] op_sel_hi:[1,0,1]
	v_mov_b32_e32 v135, v115
	s_waitcnt lgkmcnt(0)
	v_pk_fma_f32 v[132:133], v[28:29], v[194:195], v[132:133] op_sel_hi:[1,0,1]
	v_pk_add_f32 v[114:115], v[134:135], v[130:131]
	v_pk_fma_f32 v[132:133], v[98:99], v[194:195], v[132:133] op_sel:[0,1,0]
	v_pk_mul_f32 v[128:129], v[112:113], v[114:115]
	v_mov_b32_e32 v232, v197
	v_pk_fma_f32 v[132:133], v[30:31], v[196:197], v[132:133] op_sel_hi:[1,0,1]
	v_pk_fma_f32 v[130:131], v[94:95], v[114:115], v[128:129] op_sel:[0,0,1] op_sel_hi:[1,1,0] neg_lo:[0,0,1] neg_hi:[0,0,1]
	v_pk_fma_f32 v[114:115], v[94:95], v[114:115], v[128:129] op_sel:[0,0,1] op_sel_hi:[1,1,0]
	s_addk_i32 s31, 0x800
	v_pk_fma_f32 v[132:133], v[96:97], v[232:233], v[132:133] op_sel_hi:[1,0,1]
	v_mov_b32_e32 v131, v115
	s_cmpk_lg_i32 s31, 0x2000
	v_pk_add_f32 v[114:115], v[130:131], v[132:133]
	s_cbranch_scc1 .LBB0_298
	s_ashr_i32 s31, s30, 31
	s_lshl_b64 s[30:31], s[30:31], 19
	s_lshl_b32 s34, s62, 12
	s_or_b32 s30, s30, s34
	v_lshl_add_u64 v[16:17], s[30:31], 0, v[92:93]
	v_lshl_add_u64 v[16:17], v[16:17], 3, s[28:29]
	v_cndmask_b32_e64 v80, v125, v126, s[8:9]
	global_store_dwordx2 v[16:17], v[114:115], off
	v_lshl_add_u64 v[16:17], s[72:73], 0, v[80:81]
	v_mov_b32_e32 v89, v81
	v_lshl_add_u64 v[16:17], v[16:17], 0, v[88:89]
	v_lshl_add_u64 v[16:17], v[90:91], 4, v[16:17]
	v_mov_b32_e32 v83, v81
	v_lshl_add_u64 v[16:17], v[16:17], 0, v[82:83]
	v_add_co_u32_e32 v16, vcc, 0x1000, v16
	s_add_i32 s56, s56, s78
	s_nop 0
	v_addc_co_u32_e32 v17, vcc, 0, v17, vcc
	s_cmpk_gt_i32 s56, 0x7ff
	s_barrier
	s_cbranch_scc0 .LBB0_285

.LBB0_322:
	v_cndmask_b32_e64 v70, v185, v186, s[6:7]
	v_lshl_add_u64 v[64:65], s[72:73], 0, v[70:71]
	v_mov_b32_e32 v85, v71
	v_lshl_add_u64 v[64:65], v[64:65], 0, v[84:85]
	v_lshl_add_u64 v[64:65], v[86:87], 4, v[64:65]
	v_mov_b32_e32 v77, v71
	v_lshl_add_u64 v[64:65], v[64:65], 0, v[76:77]
	v_add_co_u32_e32 v32, vcc, 0x1000, v64
	s_add_i32 s47, s47, s78
	s_nop 0
	v_addc_co_u32_e32 v33, vcc, 0, v65, vcc
	s_cmpk_lt_i32 s47, 0x900
	s_barrier
	s_cbranch_scc0 .LBB0_364
.LBB0_323:
	v_lshl_add_u32 v32, s47, 3, v170
	v_mul_hi_i32 v33, v32, s4
	v_lshrrev_b32_e32 v34, 31, v33
	v_ashrrev_i32_e32 v33, 8, v33
	v_add_u32_e32 v33, v33, v34
	v_mul_i32_i24_e32 v34, 0x5fa, v33
	v_and_b32_e32 v35, 31, v33
	v_sub_u32_e32 v34, v32, v34
	v_cmp_gt_u32_e64 s[6:7], 32, v33
	v_mul_u32_u24_e32 v35, 0x300000, v35
	v_lshlrev_b32_e32 v84, 2, v35
	v_cndmask_b32_e64 v33, v179, v180, s[6:7]
	v_cndmask_b32_e64 v32, v181, v182, s[6:7]
	v_mov_b32_e32 v85, v71
	v_lshlrev_b32_e32 v86, 9, v34
	v_lshl_add_u64 v[32:33], v[32:33], 0, v[84:85]
	v_ashrrev_i32_e32 v87, 31, v86
	v_lshl_add_u64 v[32:33], v[86:87], 4, v[32:33]
	v_lshl_add_u64 v[44:45], v[32:33], 0, v[78:79]
	v_add_co_u32_e32 v42, vcc, s5, v44
	v_lshl_add_u64 v[40:41], v[44:45], 0, s[18:19]
	s_nop 0
	v_addc_co_u32_e32 v43, vcc, 0, v45, vcc
	v_add_co_u32_e32 v56, vcc, 0xd000, v44
	s_nop 0
	v_addc_co_u32_e32 v57, vcc, 0, v45, vcc
	s_nop 0
	s_cmpk_lt_i32 s47, 0x800
	s_cselect_b64 s[36:37], -1, 0
	s_cmpk_gt_i32 s47, 0x7ff
	s_cselect_b64 s[34:35], -1, 0
	s_mov_b64 s[8:9], -1
	s_and_b64 vcc, exec, s[34:35]
	s_cbranch_vccz .LBB0_325
	s_add_i32 s8, s47, 0xfffff800
	s_lshr_b32 s20, s8, 3
	s_and_b32 s8, s8, -8
	s_add_i32 s63, s8, 0x4000
	s_mov_b64 s[8:9], 0

.LBB0_412:
	s_cmp_lt_u32 s33, 64
	s_cbranch_scc1 .Lcpyb_end
	v_lshrrev_b32_e32 v21, 6, v174
	v_and_b32_e32 v22, 63, v174
	v_lshlrev_b32_e32 v22, 4, v22
	v_readfirstlane_b32 s80, v21
	v_add_u32_e32 v23, 0x1000, v22
	v_readfirstlane_b32 s92, v235
	v_readfirstlane_b32 s93, v236
	v_readfirstlane_b32 s94, v237
	v_readfirstlane_b32 s95, v238
	v_readfirstlane_b32 s98, v239
	v_readfirstlane_b32 s99, v240
	s_add_i32 s80, s80, s33
	s_add_i32 s80, s80, 0x51c8
	s_sub_i32 s100, s78, 8
	s_lshl_b32 s100, s100, 3
.Lcpyb_loop:
	s_add_i32 s101, s80, s100
	s_cmp_lt_u32 s101, 0x6d60
	s_cbranch_scc0 .Lcpyb_tail
	s_mul_hi_u32 s81, s80, 0x2ad5802b
	s_lshr_b32 s81, s81, 8
	s_mul_i32 s82, s81, 0x5fa
	s_sub_i32 s82, s80, s82
	s_lshl_b32 s82, s82, 13
	s_and_b32 s83, s81, 31
	s_mul_i32 s83, s83, 0xc00000
	s_add_i32 s82, s82, s83
	s_cmp_lt_u32 s81, 32
	s_cselect_b32 s84, s92, s94
	s_cselect_b32 s85, s93, s95
	s_mov_b32 s83, 0x1f210000
	s_cselect_b32 s83, 0x7210000, s83
	s_add_u32 s84, s84, s82
	s_addc_u32 s85, s85, 0
	s_add_u32 s84, s84, 0xc000
	s_addc_u32 s85, s85, 0
	s_add_u32 s83, s83, s82
	s_add_u32 s86, s98, s83
	s_addc_u32 s87, s99, 0
	s_mul_hi_u32 s81, s101, 0x2ad5802b
	s_lshr_b32 s81, s81, 8
	s_mul_i32 s82, s81, 0x5fa
	s_sub_i32 s82, s101, s82
	s_lshl_b32 s82, s82, 13
	s_and_b32 s83, s81, 31
	s_mul_i32 s83, s83, 0xc00000
	s_add_i32 s82, s82, s83
	s_cmp_lt_u32 s81, 32
	s_cselect_b32 s88, s92, s94
	s_cselect_b32 s89, s93, s95
	s_mov_b32 s83, 0x1f210000
	s_cselect_b32 s83, 0x7210000, s83
	s_add_u32 s88, s88, s82
	s_addc_u32 s89, s89, 0
	s_add_u32 s88, s88, 0xc000
	s_addc_u32 s89, s89, 0
	s_add_u32 s83, s83, s82
	s_add_u32 s90, s98, s83
	s_addc_u32 s91, s99, 0
	global_load_dwordx4 v[64:67], v22, s[84:85] nt
	global_load_dwordx4 v[68:71], v22, s[84:85] offset:1024 nt
	global_load_dwordx4 v[72:75], v22, s[84:85] offset:2048 nt
	global_load_dwordx4 v[76:79], v22, s[84:85] offset:3072 nt
	global_load_dwordx4 v[80:83], v23, s[84:85] nt
	global_load_dwordx4 v[84:87], v23, s[84:85] offset:1024 nt
	global_load_dwordx4 v[88:91], v23, s[84:85] offset:2048 nt
	global_load_dwordx4 v[92:95], v23, s[84:85] offset:3072 nt
	global_load_dwordx4 v[96:99], v22, s[88:89] nt
	global_load_dwordx4 v[100:103], v22, s[88:89] offset:1024 nt
	global_load_dwordx4 v[104:107], v22, s[88:89] offset:2048 nt
	global_load_dwordx4 v[108:111], v22, s[88:89] offset:3072 nt
	global_load_dwordx4 v[112:115], v23, s[88:89] nt
	global_load_dwordx4 v[116:119], v23, s[88:89] offset:1024 nt
	global_load_dwordx4 v[120:123], v23, s[88:89] offset:2048 nt
	global_load_dwordx4 v[124:127], v23, s[88:89] offset:3072 nt
	s_waitcnt vmcnt(15)
	global_store_dwordx4 v22, v[64:67], s[86:87] nt
	s_waitcnt vmcnt(15)
	global_store_dwordx4 v22, v[68:71], s[86:87] offset:1024 nt
	s_waitcnt vmcnt(15)
	global_store_dwordx4 v22, v[72:75], s[86:87] offset:2048 nt
	s_waitcnt vmcnt(15)
	global_store_dwordx4 v22, v[76:79], s[86:87] offset:3072 nt
	s_waitcnt vmcnt(15)
	global_store_dwordx4 v23, v[80:83], s[86:87] nt
	s_waitcnt vmcnt(15)
	global_store_dwordx4 v23, v[84:87], s[86:87] offset:1024 nt
	s_waitcnt vmcnt(15)
	global_store_dwordx4 v23, v[88:91], s[86:87] offset:2048 nt
	s_waitcnt vmcnt(15)
	global_store_dwordx4 v23, v[92:95], s[86:87] offset:3072 nt
	s_waitcnt vmcnt(15)
	global_store_dwordx4 v22, v[96:99], s[90:91] nt
	s_waitcnt vmcnt(15)
	global_store_dwordx4 v22, v[100:103], s[90:91] offset:1024 nt
	s_waitcnt vmcnt(15)
	global_store_dwordx4 v22, v[104:107], s[90:91] offset:2048 nt
	s_waitcnt vmcnt(15)
	global_store_dwordx4 v22, v[108:111], s[90:91] offset:3072 nt
	s_waitcnt vmcnt(15)
	global_store_dwordx4 v23, v[112:115], s[90:91] nt
	s_waitcnt vmcnt(15)
	global_store_dwordx4 v23, v[116:119], s[90:91] offset:1024 nt
	s_waitcnt vmcnt(15)
	global_store_dwordx4 v23, v[120:123], s[90:91] offset:2048 nt
	s_waitcnt vmcnt(15)
	global_store_dwordx4 v23, v[124:127], s[90:91] offset:3072 nt
	s_add_i32 s80, s101, s100
	s_branch .Lcpyb_loop
.Lcpyb_tail:
	s_cmp_lt_u32 s80, 0x6d60
	s_cbranch_scc0 .Lcpyb_end
	s_mul_hi_u32 s81, s80, 0x2ad5802b
	s_lshr_b32 s81, s81, 8
	s_mul_i32 s82, s81, 0x5fa
	s_sub_i32 s82, s80, s82
	s_lshl_b32 s82, s82, 13
	s_and_b32 s83, s81, 31
	s_mul_i32 s83, s83, 0xc00000
	s_add_i32 s82, s82, s83
	s_cmp_lt_u32 s81, 32
	s_cselect_b32 s84, s92, s94
	s_cselect_b32 s85, s93, s95
	s_mov_b32 s83, 0x1f210000
	s_cselect_b32 s83, 0x7210000, s83
	s_add_u32 s84, s84, s82
	s_addc_u32 s85, s85, 0
	s_add_u32 s84, s84, 0xc000
	s_addc_u32 s85, s85, 0
	s_add_u32 s83, s83, s82
	s_add_u32 s86, s98, s83
	s_addc_u32 s87, s99, 0
	global_load_dwordx4 v[64:67], v22, s[84:85] nt
	global_load_dwordx4 v[68:71], v22, s[84:85] offset:1024 nt
	global_load_dwordx4 v[72:75], v22, s[84:85] offset:2048 nt
	global_load_dwordx4 v[76:79], v22, s[84:85] offset:3072 nt
	global_load_dwordx4 v[80:83], v23, s[84:85] nt
	global_load_dwordx4 v[84:87], v23, s[84:85] offset:1024 nt
	global_load_dwordx4 v[88:91], v23, s[84:85] offset:2048 nt
	global_load_dwordx4 v[92:95], v23, s[84:85] offset:3072 nt
	s_waitcnt vmcnt(7)
	global_store_dwordx4 v22, v[64:67], s[86:87] nt
	s_waitcnt vmcnt(7)
	global_store_dwordx4 v22, v[68:71], s[86:87] offset:1024 nt
	s_waitcnt vmcnt(7)
	global_store_dwordx4 v22, v[72:75], s[86:87] offset:2048 nt
	s_waitcnt vmcnt(7)
	global_store_dwordx4 v22, v[76:79], s[86:87] offset:3072 nt
	s_waitcnt vmcnt(7)
	global_store_dwordx4 v23, v[80:83], s[86:87] nt
	s_waitcnt vmcnt(7)
	global_store_dwordx4 v23, v[84:87], s[86:87] offset:1024 nt
	s_waitcnt vmcnt(7)
	global_store_dwordx4 v23, v[88:91], s[86:87] offset:2048 nt
	s_waitcnt vmcnt(7)
	global_store_dwordx4 v23, v[92:95], s[86:87] offset:3072 nt

.LBB0_452:
	s_cmp_lt_u32 s33, 1200
	s_cbranch_scc1 .Lcpyc_end
	v_lshrrev_b32_e32 v21, 6, v174
	v_and_b32_e32 v22, 63, v174
	v_lshlrev_b32_e32 v22, 4, v22
	v_readfirstlane_b32 s80, v21
	v_add_u32_e32 v23, 0x1000, v22
	v_readfirstlane_b32 s92, v235
	v_readfirstlane_b32 s93, v236
	v_readfirstlane_b32 s94, v237
	v_readfirstlane_b32 s95, v238
	v_readfirstlane_b32 s98, v239
	v_readfirstlane_b32 s99, v240
	s_add_i32 s80, s80, s33
	s_add_i32 s80, s80, 0x68b0
	s_sub_i32 s100, s78, 150
	s_lshl_b32 s100, s100, 3
.Lcpyc_loop:
	s_add_i32 s101, s80, s100
	s_cmp_lt_u32 s101, 0x7d00
	s_cbranch_scc0 .Lcpyc_tail
	s_mul_hi_u32 s81, s80, 0x2ad5802b
	s_lshr_b32 s81, s81, 8
	s_mul_i32 s82, s81, 0x5fa
	s_sub_i32 s82, s80, s82
	s_lshl_b32 s82, s82, 13
	s_and_b32 s83, s81, 31
	s_mul_i32 s83, s83, 0xc00000
	s_add_i32 s82, s82, s83
	s_cmp_lt_u32 s81, 32
	s_cselect_b32 s84, s92, s94
	s_cselect_b32 s85, s93, s95
	s_mov_b32 s83, 0x1f210000
	s_cselect_b32 s83, 0x7210000, s83
	s_add_u32 s84, s84, s82
	s_addc_u32 s85, s85, 0
	s_add_u32 s84, s84, 0xc000
	s_addc_u32 s85, s85, 0
	s_add_u32 s83, s83, s82
	s_add_u32 s86, s98, s83
	s_addc_u32 s87, s99, 0
	s_mul_hi_u32 s81, s101, 0x2ad5802b
	s_lshr_b32 s81, s81, 8
	s_mul_i32 s82, s81, 0x5fa
	s_sub_i32 s82, s101, s82
	s_lshl_b32 s82, s82, 13
	s_and_b32 s83, s81, 31
	s_mul_i32 s83, s83, 0xc00000
	s_add_i32 s82, s82, s83
	s_cmp_lt_u32 s81, 32
	s_cselect_b32 s88, s92, s94
	s_cselect_b32 s89, s93, s95
	s_mov_b32 s83, 0x1f210000
	s_cselect_b32 s83, 0x7210000, s83
	s_add_u32 s88, s88, s82
	s_addc_u32 s89, s89, 0
	s_add_u32 s88, s88, 0xc000
	s_addc_u32 s89, s89, 0
	s_add_u32 s83, s83, s82
	s_add_u32 s90, s98, s83
	s_addc_u32 s91, s99, 0
	global_load_dwordx4 v[64:67], v22, s[84:85] nt
	global_load_dwordx4 v[68:71], v22, s[84:85] offset:1024 nt
	global_load_dwordx4 v[72:75], v22, s[84:85] offset:2048 nt
	global_load_dwordx4 v[76:79], v22, s[84:85] offset:3072 nt
	global_load_dwordx4 v[80:83], v23, s[84:85] nt
	global_load_dwordx4 v[84:87], v23, s[84:85] offset:1024 nt
	global_load_dwordx4 v[88:91], v23, s[84:85] offset:2048 nt
	global_load_dwordx4 v[92:95], v23, s[84:85] offset:3072 nt
	global_load_dwordx4 v[96:99], v22, s[88:89] nt
	global_load_dwordx4 v[100:103], v22, s[88:89] offset:1024 nt
	global_load_dwordx4 v[104:107], v22, s[88:89] offset:2048 nt
	global_load_dwordx4 v[108:111], v22, s[88:89] offset:3072 nt
	global_load_dwordx4 v[112:115], v23, s[88:89] nt
	global_load_dwordx4 v[116:119], v23, s[88:89] offset:1024 nt
	global_load_dwordx4 v[120:123], v23, s[88:89] offset:2048 nt
	global_load_dwordx4 v[124:127], v23, s[88:89] offset:3072 nt
	s_waitcnt vmcnt(15)
	global_store_dwordx4 v22, v[64:67], s[86:87] nt
	s_waitcnt vmcnt(15)
	global_store_dwordx4 v22, v[68:71], s[86:87] offset:1024 nt
	s_waitcnt vmcnt(15)
	global_store_dwordx4 v22, v[72:75], s[86:87] offset:2048 nt
	s_waitcnt vmcnt(15)
	global_store_dwordx4 v22, v[76:79], s[86:87] offset:3072 nt
	s_waitcnt vmcnt(15)
	global_store_dwordx4 v23, v[80:83], s[86:87] nt
	s_waitcnt vmcnt(15)
	global_store_dwordx4 v23, v[84:87], s[86:87] offset:1024 nt
	s_waitcnt vmcnt(15)
	global_store_dwordx4 v23, v[88:91], s[86:87] offset:2048 nt
	s_waitcnt vmcnt(15)
	global_store_dwordx4 v23, v[92:95], s[86:87] offset:3072 nt
	s_waitcnt vmcnt(15)
	global_store_dwordx4 v22, v[96:99], s[90:91] nt
	s_waitcnt vmcnt(15)
	global_store_dwordx4 v22, v[100:103], s[90:91] offset:1024 nt
	s_waitcnt vmcnt(15)
	global_store_dwordx4 v22, v[104:107], s[90:91] offset:2048 nt
	s_waitcnt vmcnt(15)
	global_store_dwordx4 v22, v[108:111], s[90:91] offset:3072 nt
	s_waitcnt vmcnt(15)
	global_store_dwordx4 v23, v[112:115], s[90:91] nt
	s_waitcnt vmcnt(15)
	global_store_dwordx4 v23, v[116:119], s[90:91] offset:1024 nt
	s_waitcnt vmcnt(15)
	global_store_dwordx4 v23, v[120:123], s[90:91] offset:2048 nt
	s_waitcnt vmcnt(15)
	global_store_dwordx4 v23, v[124:127], s[90:91] offset:3072 nt
	s_add_i32 s80, s101, s100
	s_branch .Lcpyc_loop
.Lcpyc_tail:
	s_cmp_lt_u32 s80, 0x7d00
	s_cbranch_scc0 .Lcpyc_end
	s_mul_hi_u32 s81, s80, 0x2ad5802b
	s_lshr_b32 s81, s81, 8
	s_mul_i32 s82, s81, 0x5fa
	s_sub_i32 s82, s80, s82
	s_lshl_b32 s82, s82, 13
	s_and_b32 s83, s81, 31
	s_mul_i32 s83, s83, 0xc00000
	s_add_i32 s82, s82, s83
	s_cmp_lt_u32 s81, 32
	s_cselect_b32 s84, s92, s94
	s_cselect_b32 s85, s93, s95
	s_mov_b32 s83, 0x1f210000
	s_cselect_b32 s83, 0x7210000, s83
	s_add_u32 s84, s84, s82
	s_addc_u32 s85, s85, 0
	s_add_u32 s84, s84, 0xc000
	s_addc_u32 s85, s85, 0
	s_add_u32 s83, s83, s82
	s_add_u32 s86, s98, s83
	s_addc_u32 s87, s99, 0
	global_load_dwordx4 v[64:67], v22, s[84:85] nt
	global_load_dwordx4 v[68:71], v22, s[84:85] offset:1024 nt
	global_load_dwordx4 v[72:75], v22, s[84:85] offset:2048 nt
	global_load_dwordx4 v[76:79], v22, s[84:85] offset:3072 nt
	global_load_dwordx4 v[80:83], v23, s[84:85] nt
	global_load_dwordx4 v[84:87], v23, s[84:85] offset:1024 nt
	global_load_dwordx4 v[88:91], v23, s[84:85] offset:2048 nt
	global_load_dwordx4 v[92:95], v23, s[84:85] offset:3072 nt
	s_waitcnt vmcnt(7)
	global_store_dwordx4 v22, v[64:67], s[86:87] nt
	s_waitcnt vmcnt(7)
	global_store_dwordx4 v22, v[68:71], s[86:87] offset:1024 nt
	s_waitcnt vmcnt(7)
	global_store_dwordx4 v22, v[72:75], s[86:87] offset:2048 nt
	s_waitcnt vmcnt(7)
	global_store_dwordx4 v22, v[76:79], s[86:87] offset:3072 nt
	s_waitcnt vmcnt(7)
	global_store_dwordx4 v23, v[80:83], s[86:87] nt
	s_waitcnt vmcnt(7)
	global_store_dwordx4 v23, v[84:87], s[86:87] offset:1024 nt
	s_waitcnt vmcnt(7)
	global_store_dwordx4 v23, v[88:91], s[86:87] offset:2048 nt
	s_waitcnt vmcnt(7)
	global_store_dwordx4 v23, v[92:95], s[86:87] offset:3072 nt

.LBB0_514:
	s_cmp_lt_u32 s33, 32
	s_cbranch_scc1 .Lcpy2_end
	v_lshrrev_b32_e32 v21, 6, v174
	v_and_b32_e32 v22, 63, v174
	v_lshlrev_b32_e32 v22, 4, v22
	v_readfirstlane_b32 s80, v21
	v_add_u32_e32 v23, 0x1000, v22
	v_readfirstlane_b32 s92, v235
	v_readfirstlane_b32 s93, v236
	v_readfirstlane_b32 s94, v237
	v_readfirstlane_b32 s95, v238
	v_readfirstlane_b32 s98, v239
	v_readfirstlane_b32 s99, v240
	s_add_i32 s80, s80, s33
	s_add_i32 s80, s80, 0x7ce0
	s_sub_i32 s100, s78, 4
	s_lshl_b32 s100, s100, 3
.Lcpy2_loop:
	s_add_i32 s101, s80, s100
	s_cmp_lt_u32 s101, 0xbf68
	s_cbranch_scc0 .Lcpy2_tail
	s_mul_hi_u32 s81, s80, 0x2ad5802b
	s_lshr_b32 s81, s81, 8
	s_mul_i32 s82, s81, 0x5fa
	s_sub_i32 s82, s80, s82
	s_lshl_b32 s82, s82, 13
	s_and_b32 s83, s81, 31
	s_mul_i32 s83, s83, 0xc00000
	s_add_i32 s82, s82, s83
	s_cmp_lt_u32 s81, 32
	s_cselect_b32 s84, s92, s94
	s_cselect_b32 s85, s93, s95
	s_mov_b32 s83, 0x1f210000
	s_cselect_b32 s83, 0x7210000, s83
	s_add_u32 s84, s84, s82
	s_addc_u32 s85, s85, 0
	s_add_u32 s84, s84, 0xc000
	s_addc_u32 s85, s85, 0
	s_add_u32 s83, s83, s82
	s_add_u32 s86, s98, s83
	s_addc_u32 s87, s99, 0
	s_mul_hi_u32 s81, s101, 0x2ad5802b
	s_lshr_b32 s81, s81, 8
	s_mul_i32 s82, s81, 0x5fa
	s_sub_i32 s82, s101, s82
	s_lshl_b32 s82, s82, 13
	s_and_b32 s83, s81, 31
	s_mul_i32 s83, s83, 0xc00000
	s_add_i32 s82, s82, s83
	s_cmp_lt_u32 s81, 32
	s_cselect_b32 s88, s92, s94
	s_cselect_b32 s89, s93, s95
	s_mov_b32 s83, 0x1f210000
	s_cselect_b32 s83, 0x7210000, s83
	s_add_u32 s88, s88, s82
	s_addc_u32 s89, s89, 0
	s_add_u32 s88, s88, 0xc000
	s_addc_u32 s89, s89, 0
	s_add_u32 s83, s83, s82
	s_add_u32 s90, s98, s83
	s_addc_u32 s91, s99, 0
	global_load_dwordx4 v[64:67], v22, s[84:85] nt
	global_load_dwordx4 v[68:71], v22, s[84:85] offset:1024 nt
	global_load_dwordx4 v[72:75], v22, s[84:85] offset:2048 nt
	global_load_dwordx4 v[76:79], v22, s[84:85] offset:3072 nt
	global_load_dwordx4 v[80:83], v23, s[84:85] nt
	global_load_dwordx4 v[84:87], v23, s[84:85] offset:1024 nt
	global_load_dwordx4 v[88:91], v23, s[84:85] offset:2048 nt
	global_load_dwordx4 v[92:95], v23, s[84:85] offset:3072 nt
	global_load_dwordx4 v[96:99], v22, s[88:89] nt
	global_load_dwordx4 v[100:103], v22, s[88:89] offset:1024 nt
	global_load_dwordx4 v[104:107], v22, s[88:89] offset:2048 nt
	global_load_dwordx4 v[108:111], v22, s[88:89] offset:3072 nt
	global_load_dwordx4 v[112:115], v23, s[88:89] nt
	global_load_dwordx4 v[116:119], v23, s[88:89] offset:1024 nt
	global_load_dwordx4 v[120:123], v23, s[88:89] offset:2048 nt
	global_load_dwordx4 v[124:127], v23, s[88:89] offset:3072 nt
	s_waitcnt vmcnt(15)
	global_store_dwordx4 v22, v[64:67], s[86:87] nt
	s_waitcnt vmcnt(15)
	global_store_dwordx4 v22, v[68:71], s[86:87] offset:1024 nt
	s_waitcnt vmcnt(15)
	global_store_dwordx4 v22, v[72:75], s[86:87] offset:2048 nt
	s_waitcnt vmcnt(15)
	global_store_dwordx4 v22, v[76:79], s[86:87] offset:3072 nt
	s_waitcnt vmcnt(15)
	global_store_dwordx4 v23, v[80:83], s[86:87] nt
	s_waitcnt vmcnt(15)
	global_store_dwordx4 v23, v[84:87], s[86:87] offset:1024 nt
	s_waitcnt vmcnt(15)
	global_store_dwordx4 v23, v[88:91], s[86:87] offset:2048 nt
	s_waitcnt vmcnt(15)
	global_store_dwordx4 v23, v[92:95], s[86:87] offset:3072 nt
	s_waitcnt vmcnt(15)
	global_store_dwordx4 v22, v[96:99], s[90:91] nt
	s_waitcnt vmcnt(15)
	global_store_dwordx4 v22, v[100:103], s[90:91] offset:1024 nt
	s_waitcnt vmcnt(15)
	global_store_dwordx4 v22, v[104:107], s[90:91] offset:2048 nt
	s_waitcnt vmcnt(15)
	global_store_dwordx4 v22, v[108:111], s[90:91] offset:3072 nt
	s_waitcnt vmcnt(15)
	global_store_dwordx4 v23, v[112:115], s[90:91] nt
	s_waitcnt vmcnt(15)
	global_store_dwordx4 v23, v[116:119], s[90:91] offset:1024 nt
	s_waitcnt vmcnt(15)
	global_store_dwordx4 v23, v[120:123], s[90:91] offset:2048 nt
	s_waitcnt vmcnt(15)
	global_store_dwordx4 v23, v[124:127], s[90:91] offset:3072 nt
	s_add_i32 s80, s101, s100
	s_branch .Lcpy2_loop
.Lcpy2_tail:
	s_cmp_lt_u32 s80, 0xbf68
	s_cbranch_scc0 .Lcpy2_end
	s_mul_hi_u32 s81, s80, 0x2ad5802b
	s_lshr_b32 s81, s81, 8
	s_mul_i32 s82, s81, 0x5fa
	s_sub_i32 s82, s80, s82
	s_lshl_b32 s82, s82, 13
	s_and_b32 s83, s81, 31
	s_mul_i32 s83, s83, 0xc00000
	s_add_i32 s82, s82, s83
	s_cmp_lt_u32 s81, 32
	s_cselect_b32 s84, s92, s94
	s_cselect_b32 s85, s93, s95
	s_mov_b32 s83, 0x1f210000
	s_cselect_b32 s83, 0x7210000, s83
	s_add_u32 s84, s84, s82
	s_addc_u32 s85, s85, 0
	s_add_u32 s84, s84, 0xc000
	s_addc_u32 s85, s85, 0
	s_add_u32 s83, s83, s82
	s_add_u32 s86, s98, s83
	s_addc_u32 s87, s99, 0
	global_load_dwordx4 v[64:67], v22, s[84:85] nt
	global_load_dwordx4 v[68:71], v22, s[84:85] offset:1024 nt
	global_load_dwordx4 v[72:75], v22, s[84:85] offset:2048 nt
	global_load_dwordx4 v[76:79], v22, s[84:85] offset:3072 nt
	global_load_dwordx4 v[80:83], v23, s[84:85] nt
	global_load_dwordx4 v[84:87], v23, s[84:85] offset:1024 nt
	global_load_dwordx4 v[88:91], v23, s[84:85] offset:2048 nt
	global_load_dwordx4 v[92:95], v23, s[84:85] offset:3072 nt
	s_waitcnt vmcnt(7)
	global_store_dwordx4 v22, v[64:67], s[86:87] nt
	s_waitcnt vmcnt(7)
	global_store_dwordx4 v22, v[68:71], s[86:87] offset:1024 nt
	s_waitcnt vmcnt(7)
	global_store_dwordx4 v22, v[72:75], s[86:87] offset:2048 nt
	s_waitcnt vmcnt(7)
	global_store_dwordx4 v22, v[76:79], s[86:87] offset:3072 nt
	s_waitcnt vmcnt(7)
	global_store_dwordx4 v23, v[80:83], s[86:87] nt
	s_waitcnt vmcnt(7)
	global_store_dwordx4 v23, v[84:87], s[86:87] offset:1024 nt
	s_waitcnt vmcnt(7)
	global_store_dwordx4 v23, v[88:91], s[86:87] offset:2048 nt
	s_waitcnt vmcnt(7)
	global_store_dwordx4 v23, v[92:95], s[86:87] offset:3072 nt

.LBB0_940:
	v_readlane_b32 s4, v234, 4
	s_waitcnt lgkmcnt(1)
	v_mov_b32_e32 v8, v174
	v_readlane_b32 s5, v234, 5
	s_and_b64 vcc, exec, s[4:5]
	v_readfirstlane_b32 s4, v8
	s_cbranch_vccnz .LBB0_960
	s_sub_i32 s100, s78, s2
	s_add_i32 s100, s100, -1
	s_ashr_i32 s5, s100, 31
	s_lshr_b32 s6, s5, 29
	s_add_i32 s6, s100, s6
	s_and_b32 s7, s6, -8
	s_sub_i32 s7, s100, s7
	s_cmp_gt_i32 s7, 5
	s_cbranch_scc0 .LBB0_943
	s_mul_i32 s8, s7, 0xb2
	s_add_i32 s11, s8, 6
	s_cbranch_execz .LBB0_944
	s_branch .LBB0_945

.LBB0_947:
	s_lshl_b32 s10, s10, 5
	s_and_b32 s15, s10, 0x60
	s_mov_b64 s[10:11], 0x80
	s_add_i32 m0, s27, 0x18000
	v_lshl_add_u64 v[6:7], v[6:7], 0, s[10:11]
	s_lshl_b32 s14, s9, 13
	s_lshl_b32 s16, s15, 7
	s_waitcnt vmcnt(4)
	s_barrier
	global_load_lds_dwordx4 v[6:7], off
	v_lshl_add_u64 v[4:5], v[4:5], 0, s[10:11]
	s_add_i32 m0, s27, 0x1a000
	s_add_i32 s55, s27, 0x8000
	s_add_i32 s56, s27, 0xa000
	global_load_lds_dwordx4 v[4:5], off
	v_lshl_add_u64 v[2:3], v[2:3], 0, s[10:11]
	s_mov_b32 m0, s55
	s_add_u32 s12, s30, 0x40080
	global_load_lds_dwordx4 v[2:3], off
	v_lshl_add_u64 v[0:1], v[0:1], 0, s[10:11]
	s_mov_b32 m0, s56
	s_addc_u32 s13, s31, 0
	global_load_lds_dwordx4 v[0:1], off
	s_add_i32 m0, s27, 0x1c000
	v_lshl_add_u64 v[0:1], s[12:13], 0, v[130:131]
	global_load_lds_dwordx4 v[0:1], off
	v_lshl_add_u64 v[0:1], s[12:13], 0, v[134:135]
	s_add_i32 m0, s27, 0x1e000
	s_add_i32 s58, 0, 0x10000
	global_load_lds_dwordx4 v[0:1], off
	v_lshrrev_b32_e32 v1, 1, v8
	v_and_b32_e32 v1, 24, v1
	v_and_b32_e32 v0, 15, v8
	v_lshlrev_b32_e32 v2, 1, v1
	v_lshl_or_b32 v148, s9, 6, v0
	v_lshl_or_b32 v0, v0, 6, v2
	v_lshlrev_b32_e32 v2, 2, v8
	v_and_b32_e32 v2, 32, v2
	v_bitop3_b32 v3, v0, s14, v2 bitop3:0xde
	v_bitop3_b32 v149, v0, s16, v2 bitop3:0xde
	v_lshlrev_b32_e32 v0, 14, v9
	v_and_b32_e32 v0, 0xffff8000, v0
	v_or_b32_e32 v150, s15, v1
	v_lshl_add_u32 v0, v10, 11, v0
	v_and_b32_e32 v1, 1, v9
	v_lshl_or_b32 v0, v1, 6, v0
	v_lshl_add_u32 v136, v11, 1, v0
	v_lshlrev_b32_e32 v0, 14, v12
	v_and_b32_e32 v0, 0xffff8000, v0
	s_waitcnt vmcnt(6)
	v_lshl_add_u32 v0, v13, 11, v0
	v_and_b32_e32 v1, 1, v12
	v_lshl_or_b32 v0, v1, 6, v0
	s_add_i32 s59, 0, 0x14000
	s_sext_i32_i16 s64, s8
	s_bfe_i64 s[12:13], s[78:79], 0x200000
	s_mov_b32 s57, s100
	v_mov_b32_e32 v137, v131
	v_lshl_add_u32 v138, v14, 1, v0
	v_mov_b32_e32 v139, v131
	v_mov_b64_e32 v[140:141], 0x596
	v_mov_b64_e32 v[142:143], 0x595
	v_add_u32_e32 v151, s58, v149
	v_add_u32_e32 v152, 0, v3
	v_add_u32_e32 v153, s59, v149
	v_mov_b32_e32 v154, 0x358637bd
	s_mov_b32 s62, 0x800000
	s_movk_i32 s63, 0x1600
	s_barrier

.LBB0_960:
	s_cmp_lt_u32 s33, 96
	s_cbranch_scc1 .Lcpyd_end
	s_cmp_ge_u32 s33, 848
	s_cbranch_scc1 .Lcpyd_end
	v_lshrrev_b32_e32 v21, 6, v174
	v_and_b32_e32 v22, 63, v174
	v_lshlrev_b32_e32 v22, 4, v22
	v_readfirstlane_b32 s80, v21
	v_add_u32_e32 v23, 0x1000, v22
	v_readfirstlane_b32 s92, v235
	v_readfirstlane_b32 s93, v236
	v_readfirstlane_b32 s94, v237
	v_readfirstlane_b32 s95, v238
	v_readfirstlane_b32 s98, v239
	v_readfirstlane_b32 s99, v240
	s_add_i32 s80, s80, s33
	s_add_i32 s80, s80, 0xbf08
	s_movk_i32 s100, 752
.Lcpyd_loop:
	s_add_i32 s101, s80, s100
	s_cmp_lt_u32 s101, 0xcd14
	s_cbranch_scc0 .Lcpyd_tail
	s_mul_hi_u32 s81, s80, 0x2ad5802b
	s_lshr_b32 s81, s81, 8
	s_mul_i32 s82, s81, 0x5fa
	s_sub_i32 s82, s80, s82
	s_lshl_b32 s82, s82, 13
	s_and_b32 s83, s81, 31
	s_mul_i32 s83, s83, 0xc00000
	s_add_i32 s82, s82, s83
	s_cmp_lt_u32 s81, 32
	s_cselect_b32 s84, s92, s94
	s_cselect_b32 s85, s93, s95
	s_mov_b32 s83, 0x1f210000
	s_cselect_b32 s83, 0x7210000, s83
	s_add_u32 s84, s84, s82
	s_addc_u32 s85, s85, 0
	s_add_u32 s84, s84, 0xc000
	s_addc_u32 s85, s85, 0
	s_add_u32 s83, s83, s82
	s_add_u32 s86, s98, s83
	s_addc_u32 s87, s99, 0
	s_mul_hi_u32 s81, s101, 0x2ad5802b
	s_lshr_b32 s81, s81, 8
	s_mul_i32 s82, s81, 0x5fa
	s_sub_i32 s82, s101, s82
	s_lshl_b32 s82, s82, 13
	s_and_b32 s83, s81, 31
	s_mul_i32 s83, s83, 0xc00000
	s_add_i32 s82, s82, s83
	s_cmp_lt_u32 s81, 32
	s_cselect_b32 s88, s92, s94
	s_cselect_b32 s89, s93, s95
	s_mov_b32 s83, 0x1f210000
	s_cselect_b32 s83, 0x7210000, s83
	s_add_u32 s88, s88, s82
	s_addc_u32 s89, s89, 0
	s_add_u32 s88, s88, 0xc000
	s_addc_u32 s89, s89, 0
	s_add_u32 s83, s83, s82
	s_add_u32 s90, s98, s83
	s_addc_u32 s91, s99, 0
	global_load_dwordx4 v[64:67], v22, s[84:85] nt
	global_load_dwordx4 v[68:71], v22, s[84:85] offset:1024 nt
	global_load_dwordx4 v[72:75], v22, s[84:85] offset:2048 nt
	global_load_dwordx4 v[76:79], v22, s[84:85] offset:3072 nt
	global_load_dwordx4 v[80:83], v23, s[84:85] nt
	global_load_dwordx4 v[84:87], v23, s[84:85] offset:1024 nt
	global_load_dwordx4 v[88:91], v23, s[84:85] offset:2048 nt
	global_load_dwordx4 v[92:95], v23, s[84:85] offset:3072 nt
	global_load_dwordx4 v[96:99], v22, s[88:89] nt
	global_load_dwordx4 v[100:103], v22, s[88:89] offset:1024 nt
	global_load_dwordx4 v[104:107], v22, s[88:89] offset:2048 nt
	global_load_dwordx4 v[108:111], v22, s[88:89] offset:3072 nt
	global_load_dwordx4 v[112:115], v23, s[88:89] nt
	global_load_dwordx4 v[116:119], v23, s[88:89] offset:1024 nt
	global_load_dwordx4 v[120:123], v23, s[88:89] offset:2048 nt
	global_load_dwordx4 v[124:127], v23, s[88:89] offset:3072 nt
	s_waitcnt vmcnt(15)
	global_store_dwordx4 v22, v[64:67], s[86:87] nt
	s_waitcnt vmcnt(15)
	global_store_dwordx4 v22, v[68:71], s[86:87] offset:1024 nt
	s_waitcnt vmcnt(15)
	global_store_dwordx4 v22, v[72:75], s[86:87] offset:2048 nt
	s_waitcnt vmcnt(15)
	global_store_dwordx4 v22, v[76:79], s[86:87] offset:3072 nt
	s_waitcnt vmcnt(15)
	global_store_dwordx4 v23, v[80:83], s[86:87] nt
	s_waitcnt vmcnt(15)
	global_store_dwordx4 v23, v[84:87], s[86:87] offset:1024 nt
	s_waitcnt vmcnt(15)
	global_store_dwordx4 v23, v[88:91], s[86:87] offset:2048 nt
	s_waitcnt vmcnt(15)
	global_store_dwordx4 v23, v[92:95], s[86:87] offset:3072 nt
	s_waitcnt vmcnt(15)
	global_store_dwordx4 v22, v[96:99], s[90:91] nt
	s_waitcnt vmcnt(15)
	global_store_dwordx4 v22, v[100:103], s[90:91] offset:1024 nt
	s_waitcnt vmcnt(15)
	global_store_dwordx4 v22, v[104:107], s[90:91] offset:2048 nt
	s_waitcnt vmcnt(15)
	global_store_dwordx4 v22, v[108:111], s[90:91] offset:3072 nt
	s_waitcnt vmcnt(15)
	global_store_dwordx4 v23, v[112:115], s[90:91] nt
	s_waitcnt vmcnt(15)
	global_store_dwordx4 v23, v[116:119], s[90:91] offset:1024 nt
	s_waitcnt vmcnt(15)
	global_store_dwordx4 v23, v[120:123], s[90:91] offset:2048 nt
	s_waitcnt vmcnt(15)
	global_store_dwordx4 v23, v[124:127], s[90:91] offset:3072 nt
	s_add_i32 s80, s101, s100
	s_branch .Lcpyd_loop
.Lcpyd_tail:
	s_cmp_lt_u32 s80, 0xcd14
	s_cbranch_scc0 .Lcpyd_end
	s_mul_hi_u32 s81, s80, 0x2ad5802b
	s_lshr_b32 s81, s81, 8
	s_mul_i32 s82, s81, 0x5fa
	s_sub_i32 s82, s80, s82
	s_lshl_b32 s82, s82, 13
	s_and_b32 s83, s81, 31
	s_mul_i32 s83, s83, 0xc00000
	s_add_i32 s82, s82, s83
	s_cmp_lt_u32 s81, 32
	s_cselect_b32 s84, s92, s94
	s_cselect_b32 s85, s93, s95
	s_mov_b32 s83, 0x1f210000
	s_cselect_b32 s83, 0x7210000, s83
	s_add_u32 s84, s84, s82
	s_addc_u32 s85, s85, 0
	s_add_u32 s84, s84, 0xc000
	s_addc_u32 s85, s85, 0
	s_add_u32 s83, s83, s82
	s_add_u32 s86, s98, s83
	s_addc_u32 s87, s99, 0
	global_load_dwordx4 v[64:67], v22, s[84:85] nt
	global_load_dwordx4 v[68:71], v22, s[84:85] offset:1024 nt
	global_load_dwordx4 v[72:75], v22, s[84:85] offset:2048 nt
	global_load_dwordx4 v[76:79], v22, s[84:85] offset:3072 nt
	global_load_dwordx4 v[80:83], v23, s[84:85] nt
	global_load_dwordx4 v[84:87], v23, s[84:85] offset:1024 nt
	global_load_dwordx4 v[88:91], v23, s[84:85] offset:2048 nt
	global_load_dwordx4 v[92:95], v23, s[84:85] offset:3072 nt
	s_waitcnt vmcnt(7)
	global_store_dwordx4 v22, v[64:67], s[86:87] nt
	s_waitcnt vmcnt(7)
	global_store_dwordx4 v22, v[68:71], s[86:87] offset:1024 nt
	s_waitcnt vmcnt(7)
	global_store_dwordx4 v22, v[72:75], s[86:87] offset:2048 nt
	s_waitcnt vmcnt(7)
	global_store_dwordx4 v22, v[76:79], s[86:87] offset:3072 nt
	s_waitcnt vmcnt(7)
	global_store_dwordx4 v23, v[80:83], s[86:87] nt
	s_waitcnt vmcnt(7)
	global_store_dwordx4 v23, v[84:87], s[86:87] offset:1024 nt
	s_waitcnt vmcnt(7)
	global_store_dwordx4 v23, v[88:91], s[86:87] offset:2048 nt
	s_waitcnt vmcnt(7)
	global_store_dwordx4 v23, v[92:95], s[86:87] offset:3072 nt

.LBB0_1022:
	s_cmp_lt_u32 s33, 32
	s_cbranch_scc1 .Lcpy3_end
	v_lshrrev_b32_e32 v21, 6, v174
	v_and_b32_e32 v22, 63, v174
	v_lshlrev_b32_e32 v22, 4, v22
	v_readfirstlane_b32 s80, v21
	v_add_u32_e32 v23, 0x1000, v22
	v_readfirstlane_b32 s92, v235
	v_readfirstlane_b32 s93, v236
	v_readfirstlane_b32 s94, v237
	v_readfirstlane_b32 s95, v238
	v_readfirstlane_b32 s98, v239
	v_readfirstlane_b32 s99, v240
	s_add_i32 s80, s80, s33
	s_add_i32 s80, s80, 0xccf4
	s_sub_i32 s100, s78, 4
	s_lshl_b32 s100, s100, 3
.Lcpy3_loop:
	s_add_i32 s101, s80, s100
	s_cmp_lt_u32 s101, 0x10f7c
	s_cbranch_scc0 .Lcpy3_tail
	s_mul_hi_u32 s81, s80, 0x2ad5802b
	s_lshr_b32 s81, s81, 8
	s_mul_i32 s82, s81, 0x5fa
	s_sub_i32 s82, s80, s82
	s_lshl_b32 s82, s82, 13
	s_and_b32 s83, s81, 31
	s_mul_i32 s83, s83, 0xc00000
	s_add_i32 s82, s82, s83
	s_cmp_lt_u32 s81, 32
	s_cselect_b32 s84, s92, s94
	s_cselect_b32 s85, s93, s95
	s_mov_b32 s83, 0x1f210000
	s_cselect_b32 s83, 0x7210000, s83
	s_add_u32 s84, s84, s82
	s_addc_u32 s85, s85, 0
	s_add_u32 s84, s84, 0xc000
	s_addc_u32 s85, s85, 0
	s_add_u32 s83, s83, s82
	s_add_u32 s86, s98, s83
	s_addc_u32 s87, s99, 0
	s_mul_hi_u32 s81, s101, 0x2ad5802b
	s_lshr_b32 s81, s81, 8
	s_mul_i32 s82, s81, 0x5fa
	s_sub_i32 s82, s101, s82
	s_lshl_b32 s82, s82, 13
	s_and_b32 s83, s81, 31
	s_mul_i32 s83, s83, 0xc00000
	s_add_i32 s82, s82, s83
	s_cmp_lt_u32 s81, 32
	s_cselect_b32 s88, s92, s94
	s_cselect_b32 s89, s93, s95
	s_mov_b32 s83, 0x1f210000
	s_cselect_b32 s83, 0x7210000, s83
	s_add_u32 s88, s88, s82
	s_addc_u32 s89, s89, 0
	s_add_u32 s88, s88, 0xc000
	s_addc_u32 s89, s89, 0
	s_add_u32 s83, s83, s82
	s_add_u32 s90, s98, s83
	s_addc_u32 s91, s99, 0
	global_load_dwordx4 v[64:67], v22, s[84:85] nt
	global_load_dwordx4 v[68:71], v22, s[84:85] offset:1024 nt
	global_load_dwordx4 v[72:75], v22, s[84:85] offset:2048 nt
	global_load_dwordx4 v[76:79], v22, s[84:85] offset:3072 nt
	global_load_dwordx4 v[80:83], v23, s[84:85] nt
	global_load_dwordx4 v[84:87], v23, s[84:85] offset:1024 nt
	global_load_dwordx4 v[88:91], v23, s[84:85] offset:2048 nt
	global_load_dwordx4 v[92:95], v23, s[84:85] offset:3072 nt
	global_load_dwordx4 v[96:99], v22, s[88:89] nt
	global_load_dwordx4 v[100:103], v22, s[88:89] offset:1024 nt
	global_load_dwordx4 v[104:107], v22, s[88:89] offset:2048 nt
	global_load_dwordx4 v[108:111], v22, s[88:89] offset:3072 nt
	global_load_dwordx4 v[112:115], v23, s[88:89] nt
	global_load_dwordx4 v[116:119], v23, s[88:89] offset:1024 nt
	global_load_dwordx4 v[120:123], v23, s[88:89] offset:2048 nt
	global_load_dwordx4 v[124:127], v23, s[88:89] offset:3072 nt
	s_waitcnt vmcnt(15)
	global_store_dwordx4 v22, v[64:67], s[86:87] nt
	s_waitcnt vmcnt(15)
	global_store_dwordx4 v22, v[68:71], s[86:87] offset:1024 nt
	s_waitcnt vmcnt(15)
	global_store_dwordx4 v22, v[72:75], s[86:87] offset:2048 nt
	s_waitcnt vmcnt(15)
	global_store_dwordx4 v22, v[76:79], s[86:87] offset:3072 nt
	s_waitcnt vmcnt(15)
	global_store_dwordx4 v23, v[80:83], s[86:87] nt
	s_waitcnt vmcnt(15)
	global_store_dwordx4 v23, v[84:87], s[86:87] offset:1024 nt
	s_waitcnt vmcnt(15)
	global_store_dwordx4 v23, v[88:91], s[86:87] offset:2048 nt
	s_waitcnt vmcnt(15)
	global_store_dwordx4 v23, v[92:95], s[86:87] offset:3072 nt
	s_waitcnt vmcnt(15)
	global_store_dwordx4 v22, v[96:99], s[90:91] nt
	s_waitcnt vmcnt(15)
	global_store_dwordx4 v22, v[100:103], s[90:91] offset:1024 nt
	s_waitcnt vmcnt(15)
	global_store_dwordx4 v22, v[104:107], s[90:91] offset:2048 nt
	s_waitcnt vmcnt(15)
	global_store_dwordx4 v22, v[108:111], s[90:91] offset:3072 nt
	s_waitcnt vmcnt(15)
	global_store_dwordx4 v23, v[112:115], s[90:91] nt
	s_waitcnt vmcnt(15)
	global_store_dwordx4 v23, v[116:119], s[90:91] offset:1024 nt
	s_waitcnt vmcnt(15)
	global_store_dwordx4 v23, v[120:123], s[90:91] offset:2048 nt
	s_waitcnt vmcnt(15)
	global_store_dwordx4 v23, v[124:127], s[90:91] offset:3072 nt
	s_add_i32 s80, s101, s100
	s_branch .Lcpy3_loop
.Lcpy3_tail:
	s_cmp_lt_u32 s80, 0x10f7c
	s_cbranch_scc0 .Lcpy3_end
	s_mul_hi_u32 s81, s80, 0x2ad5802b
	s_lshr_b32 s81, s81, 8
	s_mul_i32 s82, s81, 0x5fa
	s_sub_i32 s82, s80, s82
	s_lshl_b32 s82, s82, 13
	s_and_b32 s83, s81, 31
	s_mul_i32 s83, s83, 0xc00000
	s_add_i32 s82, s82, s83
	s_cmp_lt_u32 s81, 32
	s_cselect_b32 s84, s92, s94
	s_cselect_b32 s85, s93, s95
	s_mov_b32 s83, 0x1f210000
	s_cselect_b32 s83, 0x7210000, s83
	s_add_u32 s84, s84, s82
	s_addc_u32 s85, s85, 0
	s_add_u32 s84, s84, 0xc000
	s_addc_u32 s85, s85, 0
	s_add_u32 s83, s83, s82
	s_add_u32 s86, s98, s83
	s_addc_u32 s87, s99, 0
	global_load_dwordx4 v[64:67], v22, s[84:85] nt
	global_load_dwordx4 v[68:71], v22, s[84:85] offset:1024 nt
	global_load_dwordx4 v[72:75], v22, s[84:85] offset:2048 nt
	global_load_dwordx4 v[76:79], v22, s[84:85] offset:3072 nt
	global_load_dwordx4 v[80:83], v23, s[84:85] nt
	global_load_dwordx4 v[84:87], v23, s[84:85] offset:1024 nt
	global_load_dwordx4 v[88:91], v23, s[84:85] offset:2048 nt
	global_load_dwordx4 v[92:95], v23, s[84:85] offset:3072 nt
	s_waitcnt vmcnt(7)
	global_store_dwordx4 v22, v[64:67], s[86:87] nt
	s_waitcnt vmcnt(7)
	global_store_dwordx4 v22, v[68:71], s[86:87] offset:1024 nt
	s_waitcnt vmcnt(7)
	global_store_dwordx4 v22, v[72:75], s[86:87] offset:2048 nt
	s_waitcnt vmcnt(7)
	global_store_dwordx4 v22, v[76:79], s[86:87] offset:3072 nt
	s_waitcnt vmcnt(7)
	global_store_dwordx4 v23, v[80:83], s[86:87] nt
	s_waitcnt vmcnt(7)
	global_store_dwordx4 v23, v[84:87], s[86:87] offset:1024 nt
	s_waitcnt vmcnt(7)
	global_store_dwordx4 v23, v[88:91], s[86:87] offset:2048 nt
	s_waitcnt vmcnt(7)
	global_store_dwordx4 v23, v[92:95], s[86:87] offset:3072 nt

.LBB0_1288:
	s_cmp_lt_u32 s33, 1072
	s_cbranch_scc1 .Lcpye_end
	v_lshrrev_b32_e32 v21, 6, v174
	v_and_b32_e32 v22, 63, v174
	v_lshlrev_b32_e32 v22, 4, v22
	v_readfirstlane_b32 s80, v21
	v_add_u32_e32 v23, 0x1000, v22
	v_readfirstlane_b32 s92, v235
	v_readfirstlane_b32 s93, v236
	v_readfirstlane_b32 s94, v237
	v_readfirstlane_b32 s95, v238
	v_readfirstlane_b32 s98, v239
	v_readfirstlane_b32 s99, v240
	s_add_i32 s80, s80, s33
	s_add_i32 s80, s80, 0x10b4c
	s_sub_i32 s100, s78, 134
	s_lshl_b32 s100, s100, 3
.Lcpye_loop:
	s_add_i32 s101, s80, s100
	s_cmp_lt_u32 s101, 0x12110
	s_cbranch_scc0 .Lcpye_tail
	s_mul_hi_u32 s81, s80, 0x2ad5802b
	s_lshr_b32 s81, s81, 8
	s_mul_i32 s82, s81, 0x5fa
	s_sub_i32 s82, s80, s82
	s_lshl_b32 s82, s82, 13
	s_and_b32 s83, s81, 31
	s_mul_i32 s83, s83, 0xc00000
	s_add_i32 s82, s82, s83
	s_cmp_lt_u32 s81, 32
	s_cselect_b32 s84, s92, s94
	s_cselect_b32 s85, s93, s95
	s_mov_b32 s83, 0x1f210000
	s_cselect_b32 s83, 0x7210000, s83
	s_add_u32 s84, s84, s82
	s_addc_u32 s85, s85, 0
	s_add_u32 s84, s84, 0xc000
	s_addc_u32 s85, s85, 0
	s_add_u32 s83, s83, s82
	s_add_u32 s86, s98, s83
	s_addc_u32 s87, s99, 0
	s_mul_hi_u32 s81, s101, 0x2ad5802b
	s_lshr_b32 s81, s81, 8
	s_mul_i32 s82, s81, 0x5fa
	s_sub_i32 s82, s101, s82
	s_lshl_b32 s82, s82, 13
	s_and_b32 s83, s81, 31
	s_mul_i32 s83, s83, 0xc00000
	s_add_i32 s82, s82, s83
	s_cmp_lt_u32 s81, 32
	s_cselect_b32 s88, s92, s94
	s_cselect_b32 s89, s93, s95
	s_mov_b32 s83, 0x1f210000
	s_cselect_b32 s83, 0x7210000, s83
	s_add_u32 s88, s88, s82
	s_addc_u32 s89, s89, 0
	s_add_u32 s88, s88, 0xc000
	s_addc_u32 s89, s89, 0
	s_add_u32 s83, s83, s82
	s_add_u32 s90, s98, s83
	s_addc_u32 s91, s99, 0
	global_load_dwordx4 v[64:67], v22, s[84:85] nt
	global_load_dwordx4 v[68:71], v22, s[84:85] offset:1024 nt
	global_load_dwordx4 v[72:75], v22, s[84:85] offset:2048 nt
	global_load_dwordx4 v[76:79], v22, s[84:85] offset:3072 nt
	global_load_dwordx4 v[80:83], v23, s[84:85] nt
	global_load_dwordx4 v[84:87], v23, s[84:85] offset:1024 nt
	global_load_dwordx4 v[88:91], v23, s[84:85] offset:2048 nt
	global_load_dwordx4 v[92:95], v23, s[84:85] offset:3072 nt
	global_load_dwordx4 v[96:99], v22, s[88:89] nt
	global_load_dwordx4 v[100:103], v22, s[88:89] offset:1024 nt
	global_load_dwordx4 v[104:107], v22, s[88:89] offset:2048 nt
	global_load_dwordx4 v[108:111], v22, s[88:89] offset:3072 nt
	global_load_dwordx4 v[112:115], v23, s[88:89] nt
	global_load_dwordx4 v[116:119], v23, s[88:89] offset:1024 nt
	global_load_dwordx4 v[120:123], v23, s[88:89] offset:2048 nt
	global_load_dwordx4 v[124:127], v23, s[88:89] offset:3072 nt
	s_waitcnt vmcnt(15)
	global_store_dwordx4 v22, v[64:67], s[86:87] nt
	s_waitcnt vmcnt(15)
	global_store_dwordx4 v22, v[68:71], s[86:87] offset:1024 nt
	s_waitcnt vmcnt(15)
	global_store_dwordx4 v22, v[72:75], s[86:87] offset:2048 nt
	s_waitcnt vmcnt(15)
	global_store_dwordx4 v22, v[76:79], s[86:87] offset:3072 nt
	s_waitcnt vmcnt(15)
	global_store_dwordx4 v23, v[80:83], s[86:87] nt
	s_waitcnt vmcnt(15)
	global_store_dwordx4 v23, v[84:87], s[86:87] offset:1024 nt
	s_waitcnt vmcnt(15)
	global_store_dwordx4 v23, v[88:91], s[86:87] offset:2048 nt
	s_waitcnt vmcnt(15)
	global_store_dwordx4 v23, v[92:95], s[86:87] offset:3072 nt
	s_waitcnt vmcnt(15)
	global_store_dwordx4 v22, v[96:99], s[90:91] nt
	s_waitcnt vmcnt(15)
	global_store_dwordx4 v22, v[100:103], s[90:91] offset:1024 nt
	s_waitcnt vmcnt(15)
	global_store_dwordx4 v22, v[104:107], s[90:91] offset:2048 nt
	s_waitcnt vmcnt(15)
	global_store_dwordx4 v22, v[108:111], s[90:91] offset:3072 nt
	s_waitcnt vmcnt(15)
	global_store_dwordx4 v23, v[112:115], s[90:91] nt
	s_waitcnt vmcnt(15)
	global_store_dwordx4 v23, v[116:119], s[90:91] offset:1024 nt
	s_waitcnt vmcnt(15)
	global_store_dwordx4 v23, v[120:123], s[90:91] offset:2048 nt
	s_waitcnt vmcnt(15)
	global_store_dwordx4 v23, v[124:127], s[90:91] offset:3072 nt
	s_add_i32 s80, s101, s100
	s_branch .Lcpye_loop
.Lcpye_tail:
	s_cmp_lt_u32 s80, 0x12110
	s_cbranch_scc0 .Lcpye_end
	s_mul_hi_u32 s81, s80, 0x2ad5802b
	s_lshr_b32 s81, s81, 8
	s_mul_i32 s82, s81, 0x5fa
	s_sub_i32 s82, s80, s82
	s_lshl_b32 s82, s82, 13
	s_and_b32 s83, s81, 31
	s_mul_i32 s83, s83, 0xc00000
	s_add_i32 s82, s82, s83
	s_cmp_lt_u32 s81, 32
	s_cselect_b32 s84, s92, s94
	s_cselect_b32 s85, s93, s95
	s_mov_b32 s83, 0x1f210000
	s_cselect_b32 s83, 0x7210000, s83
	s_add_u32 s84, s84, s82
	s_addc_u32 s85, s85, 0
	s_add_u32 s84, s84, 0xc000
	s_addc_u32 s85, s85, 0
	s_add_u32 s83, s83, s82
	s_add_u32 s86, s98, s83
	s_addc_u32 s87, s99, 0
	global_load_dwordx4 v[64:67], v22, s[84:85] nt
	global_load_dwordx4 v[68:71], v22, s[84:85] offset:1024 nt
	global_load_dwordx4 v[72:75], v22, s[84:85] offset:2048 nt
	global_load_dwordx4 v[76:79], v22, s[84:85] offset:3072 nt
	global_load_dwordx4 v[80:83], v23, s[84:85] nt
	global_load_dwordx4 v[84:87], v23, s[84:85] offset:1024 nt
	global_load_dwordx4 v[88:91], v23, s[84:85] offset:2048 nt
	global_load_dwordx4 v[92:95], v23, s[84:85] offset:3072 nt
	s_waitcnt vmcnt(7)
	global_store_dwordx4 v22, v[64:67], s[86:87] nt
	s_waitcnt vmcnt(7)
	global_store_dwordx4 v22, v[68:71], s[86:87] offset:1024 nt
	s_waitcnt vmcnt(7)
	global_store_dwordx4 v22, v[72:75], s[86:87] offset:2048 nt
	s_waitcnt vmcnt(7)
	global_store_dwordx4 v22, v[76:79], s[86:87] offset:3072 nt
	s_waitcnt vmcnt(7)
	global_store_dwordx4 v23, v[80:83], s[86:87] nt
	s_waitcnt vmcnt(7)
	global_store_dwordx4 v23, v[84:87], s[86:87] offset:1024 nt
	s_waitcnt vmcnt(7)
	global_store_dwordx4 v23, v[88:91], s[86:87] offset:2048 nt
	s_waitcnt vmcnt(7)
	global_store_dwordx4 v23, v[92:95], s[86:87] offset:3072 nt

.LBB0_1421:
	s_cmp_lt_u32 s33, 32
	s_cbranch_scc1 .Lcpyf_end
	v_lshrrev_b32_e32 v21, 6, v174
	v_and_b32_e32 v22, 63, v174
	v_lshlrev_b32_e32 v22, 4, v22
	v_readfirstlane_b32 s80, v21
	v_add_u32_e32 v23, 0x1000, v22
	v_readfirstlane_b32 s92, v235
	v_readfirstlane_b32 s93, v236
	v_readfirstlane_b32 s94, v237
	v_readfirstlane_b32 s95, v238
	v_readfirstlane_b32 s98, v239
	v_readfirstlane_b32 s99, v240
	s_add_i32 s80, s80, s33
	s_add_i32 s80, s80, 0x120f0
	s_sub_i32 s100, s78, 4
	s_lshl_b32 s100, s100, 3
.Lcpyf_loop:
	s_add_i32 s101, s80, s100
	s_cmp_lt_u32 s101, 0x12c78
	s_cbranch_scc0 .Lcpyf_tail
	s_mul_hi_u32 s81, s80, 0x2ad5802b
	s_lshr_b32 s81, s81, 8
	s_mul_i32 s82, s81, 0x5fa
	s_sub_i32 s82, s80, s82
	s_lshl_b32 s82, s82, 13
	s_and_b32 s83, s81, 31
	s_mul_i32 s83, s83, 0xc00000
	s_add_i32 s82, s82, s83
	s_cmp_lt_u32 s81, 32
	s_cselect_b32 s84, s92, s94
	s_cselect_b32 s85, s93, s95
	s_mov_b32 s83, 0x1f210000
	s_cselect_b32 s83, 0x7210000, s83
	s_add_u32 s84, s84, s82
	s_addc_u32 s85, s85, 0
	s_add_u32 s84, s84, 0xc000
	s_addc_u32 s85, s85, 0
	s_add_u32 s83, s83, s82
	s_add_u32 s86, s98, s83
	s_addc_u32 s87, s99, 0
	s_mul_hi_u32 s81, s101, 0x2ad5802b
	s_lshr_b32 s81, s81, 8
	s_mul_i32 s82, s81, 0x5fa
	s_sub_i32 s82, s101, s82
	s_lshl_b32 s82, s82, 13
	s_and_b32 s83, s81, 31
	s_mul_i32 s83, s83, 0xc00000
	s_add_i32 s82, s82, s83
	s_cmp_lt_u32 s81, 32
	s_cselect_b32 s88, s92, s94
	s_cselect_b32 s89, s93, s95
	s_mov_b32 s83, 0x1f210000
	s_cselect_b32 s83, 0x7210000, s83
	s_add_u32 s88, s88, s82
	s_addc_u32 s89, s89, 0
	s_add_u32 s88, s88, 0xc000
	s_addc_u32 s89, s89, 0
	s_add_u32 s83, s83, s82
	s_add_u32 s90, s98, s83
	s_addc_u32 s91, s99, 0
	global_load_dwordx4 v[64:67], v22, s[84:85] nt
	global_load_dwordx4 v[68:71], v22, s[84:85] offset:1024 nt
	global_load_dwordx4 v[72:75], v22, s[84:85] offset:2048 nt
	global_load_dwordx4 v[76:79], v22, s[84:85] offset:3072 nt
	global_load_dwordx4 v[80:83], v23, s[84:85] nt
	global_load_dwordx4 v[84:87], v23, s[84:85] offset:1024 nt
	global_load_dwordx4 v[88:91], v23, s[84:85] offset:2048 nt
	global_load_dwordx4 v[92:95], v23, s[84:85] offset:3072 nt
	global_load_dwordx4 v[96:99], v22, s[88:89] nt
	global_load_dwordx4 v[100:103], v22, s[88:89] offset:1024 nt
	global_load_dwordx4 v[104:107], v22, s[88:89] offset:2048 nt
	global_load_dwordx4 v[108:111], v22, s[88:89] offset:3072 nt
	global_load_dwordx4 v[112:115], v23, s[88:89] nt
	global_load_dwordx4 v[116:119], v23, s[88:89] offset:1024 nt
	global_load_dwordx4 v[120:123], v23, s[88:89] offset:2048 nt
	global_load_dwordx4 v[124:127], v23, s[88:89] offset:3072 nt
	s_waitcnt vmcnt(15)
	global_store_dwordx4 v22, v[64:67], s[86:87] nt
	s_waitcnt vmcnt(15)
	global_store_dwordx4 v22, v[68:71], s[86:87] offset:1024 nt
	s_waitcnt vmcnt(15)
	global_store_dwordx4 v22, v[72:75], s[86:87] offset:2048 nt
	s_waitcnt vmcnt(15)
	global_store_dwordx4 v22, v[76:79], s[86:87] offset:3072 nt
	s_waitcnt vmcnt(15)
	global_store_dwordx4 v23, v[80:83], s[86:87] nt
	s_waitcnt vmcnt(15)
	global_store_dwordx4 v23, v[84:87], s[86:87] offset:1024 nt
	s_waitcnt vmcnt(15)
	global_store_dwordx4 v23, v[88:91], s[86:87] offset:2048 nt
	s_waitcnt vmcnt(15)
	global_store_dwordx4 v23, v[92:95], s[86:87] offset:3072 nt
	s_waitcnt vmcnt(15)
	global_store_dwordx4 v22, v[96:99], s[90:91] nt
	s_waitcnt vmcnt(15)
	global_store_dwordx4 v22, v[100:103], s[90:91] offset:1024 nt
	s_waitcnt vmcnt(15)
	global_store_dwordx4 v22, v[104:107], s[90:91] offset:2048 nt
	s_waitcnt vmcnt(15)
	global_store_dwordx4 v22, v[108:111], s[90:91] offset:3072 nt
	s_waitcnt vmcnt(15)
	global_store_dwordx4 v23, v[112:115], s[90:91] nt
	s_waitcnt vmcnt(15)
	global_store_dwordx4 v23, v[116:119], s[90:91] offset:1024 nt
	s_waitcnt vmcnt(15)
	global_store_dwordx4 v23, v[120:123], s[90:91] offset:2048 nt
	s_waitcnt vmcnt(15)
	global_store_dwordx4 v23, v[124:127], s[90:91] offset:3072 nt
	s_add_i32 s80, s101, s100
	s_branch .Lcpyf_loop
.Lcpyf_tail:
	s_cmp_lt_u32 s80, 0x12c78
	s_cbranch_scc0 .Lcpyf_end
	s_mul_hi_u32 s81, s80, 0x2ad5802b
	s_lshr_b32 s81, s81, 8
	s_mul_i32 s82, s81, 0x5fa
	s_sub_i32 s82, s80, s82
	s_lshl_b32 s82, s82, 13
	s_and_b32 s83, s81, 31
	s_mul_i32 s83, s83, 0xc00000
	s_add_i32 s82, s82, s83
	s_cmp_lt_u32 s81, 32
	s_cselect_b32 s84, s92, s94
	s_cselect_b32 s85, s93, s95
	s_mov_b32 s83, 0x1f210000
	s_cselect_b32 s83, 0x7210000, s83
	s_add_u32 s84, s84, s82
	s_addc_u32 s85, s85, 0
	s_add_u32 s84, s84, 0xc000
	s_addc_u32 s85, s85, 0
	s_add_u32 s83, s83, s82
	s_add_u32 s86, s98, s83
	s_addc_u32 s87, s99, 0
	global_load_dwordx4 v[64:67], v22, s[84:85] nt
	global_load_dwordx4 v[68:71], v22, s[84:85] offset:1024 nt
	global_load_dwordx4 v[72:75], v22, s[84:85] offset:2048 nt
	global_load_dwordx4 v[76:79], v22, s[84:85] offset:3072 nt
	global_load_dwordx4 v[80:83], v23, s[84:85] nt
	global_load_dwordx4 v[84:87], v23, s[84:85] offset:1024 nt
	global_load_dwordx4 v[88:91], v23, s[84:85] offset:2048 nt
	global_load_dwordx4 v[92:95], v23, s[84:85] offset:3072 nt
	s_waitcnt vmcnt(7)
	global_store_dwordx4 v22, v[64:67], s[86:87] nt
	s_waitcnt vmcnt(7)
	global_store_dwordx4 v22, v[68:71], s[86:87] offset:1024 nt
	s_waitcnt vmcnt(7)
	global_store_dwordx4 v22, v[72:75], s[86:87] offset:2048 nt
	s_waitcnt vmcnt(7)
	global_store_dwordx4 v22, v[76:79], s[86:87] offset:3072 nt
	s_waitcnt vmcnt(7)
	global_store_dwordx4 v23, v[80:83], s[86:87] nt
	s_waitcnt vmcnt(7)
	global_store_dwordx4 v23, v[84:87], s[86:87] offset:1024 nt
	s_waitcnt vmcnt(7)
	global_store_dwordx4 v23, v[88:91], s[86:87] offset:2048 nt
	s_waitcnt vmcnt(7)
	global_store_dwordx4 v23, v[92:95], s[86:87] offset:3072 nt

.LBB0_1461:
	s_cmp_lt_u32 s33, 1200
	s_cbranch_scc1 .Lcpyg_end
	v_lshrrev_b32_e32 v21, 6, v174
	v_and_b32_e32 v22, 63, v174
	v_lshlrev_b32_e32 v22, 4, v22
	v_readfirstlane_b32 s80, v21
	v_add_u32_e32 v23, 0x1000, v22
	v_readfirstlane_b32 s92, v235
	v_readfirstlane_b32 s93, v236
	v_readfirstlane_b32 s94, v237
	v_readfirstlane_b32 s95, v238
	v_readfirstlane_b32 s98, v239
	v_readfirstlane_b32 s99, v240
	s_add_i32 s80, s80, s33
	s_add_i32 s80, s80, 0x127c8
	s_sub_i32 s100, s78, 150
	s_lshl_b32 s100, s100, 3
.Lcpyg_loop:
	s_add_i32 s101, s80, s100
	s_cmp_lt_u32 s101, 0x13c18
	s_cbranch_scc0 .Lcpyg_tail
	s_mul_hi_u32 s81, s80, 0x2ad5802b
	s_lshr_b32 s81, s81, 8
	s_mul_i32 s82, s81, 0x5fa
	s_sub_i32 s82, s80, s82
	s_lshl_b32 s82, s82, 13
	s_and_b32 s83, s81, 31
	s_mul_i32 s83, s83, 0xc00000
	s_add_i32 s82, s82, s83
	s_cmp_lt_u32 s81, 32
	s_cselect_b32 s84, s92, s94
	s_cselect_b32 s85, s93, s95
	s_mov_b32 s83, 0x1f210000
	s_cselect_b32 s83, 0x7210000, s83
	s_add_u32 s84, s84, s82
	s_addc_u32 s85, s85, 0
	s_add_u32 s84, s84, 0xc000
	s_addc_u32 s85, s85, 0
	s_add_u32 s83, s83, s82
	s_add_u32 s86, s98, s83
	s_addc_u32 s87, s99, 0
	s_mul_hi_u32 s81, s101, 0x2ad5802b
	s_lshr_b32 s81, s81, 8
	s_mul_i32 s82, s81, 0x5fa
	s_sub_i32 s82, s101, s82
	s_lshl_b32 s82, s82, 13
	s_and_b32 s83, s81, 31
	s_mul_i32 s83, s83, 0xc00000
	s_add_i32 s82, s82, s83
	s_cmp_lt_u32 s81, 32
	s_cselect_b32 s88, s92, s94
	s_cselect_b32 s89, s93, s95
	s_mov_b32 s83, 0x1f210000
	s_cselect_b32 s83, 0x7210000, s83
	s_add_u32 s88, s88, s82
	s_addc_u32 s89, s89, 0
	s_add_u32 s88, s88, 0xc000
	s_addc_u32 s89, s89, 0
	s_add_u32 s83, s83, s82
	s_add_u32 s90, s98, s83
	s_addc_u32 s91, s99, 0
	global_load_dwordx4 v[64:67], v22, s[84:85] nt
	global_load_dwordx4 v[68:71], v22, s[84:85] offset:1024 nt
	global_load_dwordx4 v[72:75], v22, s[84:85] offset:2048 nt
	global_load_dwordx4 v[76:79], v22, s[84:85] offset:3072 nt
	global_load_dwordx4 v[80:83], v23, s[84:85] nt
	global_load_dwordx4 v[84:87], v23, s[84:85] offset:1024 nt
	global_load_dwordx4 v[88:91], v23, s[84:85] offset:2048 nt
	global_load_dwordx4 v[92:95], v23, s[84:85] offset:3072 nt
	global_load_dwordx4 v[96:99], v22, s[88:89] nt
	global_load_dwordx4 v[100:103], v22, s[88:89] offset:1024 nt
	global_load_dwordx4 v[104:107], v22, s[88:89] offset:2048 nt
	global_load_dwordx4 v[108:111], v22, s[88:89] offset:3072 nt
	global_load_dwordx4 v[112:115], v23, s[88:89] nt
	global_load_dwordx4 v[116:119], v23, s[88:89] offset:1024 nt
	global_load_dwordx4 v[120:123], v23, s[88:89] offset:2048 nt
	global_load_dwordx4 v[124:127], v23, s[88:89] offset:3072 nt
	s_waitcnt vmcnt(15)
	global_store_dwordx4 v22, v[64:67], s[86:87] nt
	s_waitcnt vmcnt(15)
	global_store_dwordx4 v22, v[68:71], s[86:87] offset:1024 nt
	s_waitcnt vmcnt(15)
	global_store_dwordx4 v22, v[72:75], s[86:87] offset:2048 nt
	s_waitcnt vmcnt(15)
	global_store_dwordx4 v22, v[76:79], s[86:87] offset:3072 nt
	s_waitcnt vmcnt(15)
	global_store_dwordx4 v23, v[80:83], s[86:87] nt
	s_waitcnt vmcnt(15)
	global_store_dwordx4 v23, v[84:87], s[86:87] offset:1024 nt
	s_waitcnt vmcnt(15)
	global_store_dwordx4 v23, v[88:91], s[86:87] offset:2048 nt
	s_waitcnt vmcnt(15)
	global_store_dwordx4 v23, v[92:95], s[86:87] offset:3072 nt
	s_waitcnt vmcnt(15)
	global_store_dwordx4 v22, v[96:99], s[90:91] nt
	s_waitcnt vmcnt(15)
	global_store_dwordx4 v22, v[100:103], s[90:91] offset:1024 nt
	s_waitcnt vmcnt(15)
	global_store_dwordx4 v22, v[104:107], s[90:91] offset:2048 nt
	s_waitcnt vmcnt(15)
	global_store_dwordx4 v22, v[108:111], s[90:91] offset:3072 nt
	s_waitcnt vmcnt(15)
	global_store_dwordx4 v23, v[112:115], s[90:91] nt
	s_waitcnt vmcnt(15)
	global_store_dwordx4 v23, v[116:119], s[90:91] offset:1024 nt
	s_waitcnt vmcnt(15)
	global_store_dwordx4 v23, v[120:123], s[90:91] offset:2048 nt
	s_waitcnt vmcnt(15)
	global_store_dwordx4 v23, v[124:127], s[90:91] offset:3072 nt
	s_add_i32 s80, s101, s100
	s_branch .Lcpyg_loop
.Lcpyg_tail:
	s_cmp_lt_u32 s80, 0x13c18
	s_cbranch_scc0 .Lcpyg_end
	s_mul_hi_u32 s81, s80, 0x2ad5802b
	s_lshr_b32 s81, s81, 8
	s_mul_i32 s82, s81, 0x5fa
	s_sub_i32 s82, s80, s82
	s_lshl_b32 s82, s82, 13
	s_and_b32 s83, s81, 31
	s_mul_i32 s83, s83, 0xc00000
	s_add_i32 s82, s82, s83
	s_cmp_lt_u32 s81, 32
	s_cselect_b32 s84, s92, s94
	s_cselect_b32 s85, s93, s95
	s_mov_b32 s83, 0x1f210000
	s_cselect_b32 s83, 0x7210000, s83
	s_add_u32 s84, s84, s82
	s_addc_u32 s85, s85, 0
	s_add_u32 s84, s84, 0xc000
	s_addc_u32 s85, s85, 0
	s_add_u32 s83, s83, s82
	s_add_u32 s86, s98, s83
	s_addc_u32 s87, s99, 0
	global_load_dwordx4 v[64:67], v22, s[84:85] nt
	global_load_dwordx4 v[68:71], v22, s[84:85] offset:1024 nt
	global_load_dwordx4 v[72:75], v22, s[84:85] offset:2048 nt
	global_load_dwordx4 v[76:79], v22, s[84:85] offset:3072 nt
	global_load_dwordx4 v[80:83], v23, s[84:85] nt
	global_load_dwordx4 v[84:87], v23, s[84:85] offset:1024 nt
	global_load_dwordx4 v[88:91], v23, s[84:85] offset:2048 nt
	global_load_dwordx4 v[92:95], v23, s[84:85] offset:3072 nt
	s_waitcnt vmcnt(7)
	global_store_dwordx4 v22, v[64:67], s[86:87] nt
	s_waitcnt vmcnt(7)
	global_store_dwordx4 v22, v[68:71], s[86:87] offset:1024 nt
	s_waitcnt vmcnt(7)
	global_store_dwordx4 v22, v[72:75], s[86:87] offset:2048 nt
	s_waitcnt vmcnt(7)
	global_store_dwordx4 v22, v[76:79], s[86:87] offset:3072 nt
	s_waitcnt vmcnt(7)
	global_store_dwordx4 v23, v[80:83], s[86:87] nt
	s_waitcnt vmcnt(7)
	global_store_dwordx4 v23, v[84:87], s[86:87] offset:1024 nt
	s_waitcnt vmcnt(7)
	global_store_dwordx4 v23, v[88:91], s[86:87] offset:2048 nt
	s_waitcnt vmcnt(7)
	global_store_dwordx4 v23, v[92:95], s[86:87] offset:3072 nt

.LBB0_1523:
	s_cmp_lt_u32 s33, 32
	s_cbranch_scc1 .Lcpy4_end
	v_lshrrev_b32_e32 v21, 6, v174
	v_and_b32_e32 v22, 63, v174
	v_lshlrev_b32_e32 v22, 4, v22
	v_readfirstlane_b32 s80, v21
	v_add_u32_e32 v23, 0x1000, v22
	v_readfirstlane_b32 s92, v235
	v_readfirstlane_b32 s93, v236
	v_readfirstlane_b32 s94, v237
	v_readfirstlane_b32 s95, v238
	v_readfirstlane_b32 s98, v239
	v_readfirstlane_b32 s99, v240
	s_add_i32 s80, s80, s33
	s_add_i32 s80, s80, 0x13bf8
	s_sub_i32 s100, s78, 4
	s_lshl_b32 s100, s100, 3
.Lcpy4_loop:
	s_add_i32 s101, s80, s100
	s_cmp_lt_u32 s101, 0x17e80
	s_cbranch_scc0 .Lcpy4_tail
	s_mul_hi_u32 s81, s80, 0x2ad5802b
	s_lshr_b32 s81, s81, 8
	s_mul_i32 s82, s81, 0x5fa
	s_sub_i32 s82, s80, s82
	s_lshl_b32 s82, s82, 13
	s_and_b32 s83, s81, 31
	s_mul_i32 s83, s83, 0xc00000
	s_add_i32 s82, s82, s83
	s_cmp_lt_u32 s81, 32
	s_cselect_b32 s84, s92, s94
	s_cselect_b32 s85, s93, s95
	s_mov_b32 s83, 0x1f210000
	s_cselect_b32 s83, 0x7210000, s83
	s_add_u32 s84, s84, s82
	s_addc_u32 s85, s85, 0
	s_add_u32 s84, s84, 0xc000
	s_addc_u32 s85, s85, 0
	s_add_u32 s83, s83, s82
	s_add_u32 s86, s98, s83
	s_addc_u32 s87, s99, 0
	s_mul_hi_u32 s81, s101, 0x2ad5802b
	s_lshr_b32 s81, s81, 8
	s_mul_i32 s82, s81, 0x5fa
	s_sub_i32 s82, s101, s82
	s_lshl_b32 s82, s82, 13
	s_and_b32 s83, s81, 31
	s_mul_i32 s83, s83, 0xc00000
	s_add_i32 s82, s82, s83
	s_cmp_lt_u32 s81, 32
	s_cselect_b32 s88, s92, s94
	s_cselect_b32 s89, s93, s95
	s_mov_b32 s83, 0x1f210000
	s_cselect_b32 s83, 0x7210000, s83
	s_add_u32 s88, s88, s82
	s_addc_u32 s89, s89, 0
	s_add_u32 s88, s88, 0xc000
	s_addc_u32 s89, s89, 0
	s_add_u32 s83, s83, s82
	s_add_u32 s90, s98, s83
	s_addc_u32 s91, s99, 0
	global_load_dwordx4 v[64:67], v22, s[84:85] nt
	global_load_dwordx4 v[68:71], v22, s[84:85] offset:1024 nt
	global_load_dwordx4 v[72:75], v22, s[84:85] offset:2048 nt
	global_load_dwordx4 v[76:79], v22, s[84:85] offset:3072 nt
	global_load_dwordx4 v[80:83], v23, s[84:85] nt
	global_load_dwordx4 v[84:87], v23, s[84:85] offset:1024 nt
	global_load_dwordx4 v[88:91], v23, s[84:85] offset:2048 nt
	global_load_dwordx4 v[92:95], v23, s[84:85] offset:3072 nt
	global_load_dwordx4 v[96:99], v22, s[88:89] nt
	global_load_dwordx4 v[100:103], v22, s[88:89] offset:1024 nt
	global_load_dwordx4 v[104:107], v22, s[88:89] offset:2048 nt
	global_load_dwordx4 v[108:111], v22, s[88:89] offset:3072 nt
	global_load_dwordx4 v[112:115], v23, s[88:89] nt
	global_load_dwordx4 v[116:119], v23, s[88:89] offset:1024 nt
	global_load_dwordx4 v[120:123], v23, s[88:89] offset:2048 nt
	global_load_dwordx4 v[124:127], v23, s[88:89] offset:3072 nt
	s_waitcnt vmcnt(15)
	global_store_dwordx4 v22, v[64:67], s[86:87] nt
	s_waitcnt vmcnt(15)
	global_store_dwordx4 v22, v[68:71], s[86:87] offset:1024 nt
	s_waitcnt vmcnt(15)
	global_store_dwordx4 v22, v[72:75], s[86:87] offset:2048 nt
	s_waitcnt vmcnt(15)
	global_store_dwordx4 v22, v[76:79], s[86:87] offset:3072 nt
	s_waitcnt vmcnt(15)
	global_store_dwordx4 v23, v[80:83], s[86:87] nt
	s_waitcnt vmcnt(15)
	global_store_dwordx4 v23, v[84:87], s[86:87] offset:1024 nt
	s_waitcnt vmcnt(15)
	global_store_dwordx4 v23, v[88:91], s[86:87] offset:2048 nt
	s_waitcnt vmcnt(15)
	global_store_dwordx4 v23, v[92:95], s[86:87] offset:3072 nt
	s_waitcnt vmcnt(15)
	global_store_dwordx4 v22, v[96:99], s[90:91] nt
	s_waitcnt vmcnt(15)
	global_store_dwordx4 v22, v[100:103], s[90:91] offset:1024 nt
	s_waitcnt vmcnt(15)
	global_store_dwordx4 v22, v[104:107], s[90:91] offset:2048 nt
	s_waitcnt vmcnt(15)
	global_store_dwordx4 v22, v[108:111], s[90:91] offset:3072 nt
	s_waitcnt vmcnt(15)
	global_store_dwordx4 v23, v[112:115], s[90:91] nt
	s_waitcnt vmcnt(15)
	global_store_dwordx4 v23, v[116:119], s[90:91] offset:1024 nt
	s_waitcnt vmcnt(15)
	global_store_dwordx4 v23, v[120:123], s[90:91] offset:2048 nt
	s_waitcnt vmcnt(15)
	global_store_dwordx4 v23, v[124:127], s[90:91] offset:3072 nt
	s_add_i32 s80, s101, s100
	s_branch .Lcpy4_loop
.Lcpy4_tail:
	s_cmp_lt_u32 s80, 0x17e80
	s_cbranch_scc0 .Lcpy4_end
	s_mul_hi_u32 s81, s80, 0x2ad5802b
	s_lshr_b32 s81, s81, 8
	s_mul_i32 s82, s81, 0x5fa
	s_sub_i32 s82, s80, s82
	s_lshl_b32 s82, s82, 13
	s_and_b32 s83, s81, 31
	s_mul_i32 s83, s83, 0xc00000
	s_add_i32 s82, s82, s83
	s_cmp_lt_u32 s81, 32
	s_cselect_b32 s84, s92, s94
	s_cselect_b32 s85, s93, s95
	s_mov_b32 s83, 0x1f210000
	s_cselect_b32 s83, 0x7210000, s83
	s_add_u32 s84, s84, s82
	s_addc_u32 s85, s85, 0
	s_add_u32 s84, s84, 0xc000
	s_addc_u32 s85, s85, 0
	s_add_u32 s83, s83, s82
	s_add_u32 s86, s98, s83
	s_addc_u32 s87, s99, 0
	global_load_dwordx4 v[64:67], v22, s[84:85] nt
	global_load_dwordx4 v[68:71], v22, s[84:85] offset:1024 nt
	global_load_dwordx4 v[72:75], v22, s[84:85] offset:2048 nt
	global_load_dwordx4 v[76:79], v22, s[84:85] offset:3072 nt
	global_load_dwordx4 v[80:83], v23, s[84:85] nt
	global_load_dwordx4 v[84:87], v23, s[84:85] offset:1024 nt
	global_load_dwordx4 v[88:91], v23, s[84:85] offset:2048 nt
	global_load_dwordx4 v[92:95], v23, s[84:85] offset:3072 nt
	s_waitcnt vmcnt(7)
	global_store_dwordx4 v22, v[64:67], s[86:87] nt
	s_waitcnt vmcnt(7)
	global_store_dwordx4 v22, v[68:71], s[86:87] offset:1024 nt
	s_waitcnt vmcnt(7)
	global_store_dwordx4 v22, v[72:75], s[86:87] offset:2048 nt
	s_waitcnt vmcnt(7)
	global_store_dwordx4 v22, v[76:79], s[86:87] offset:3072 nt
	s_waitcnt vmcnt(7)
	global_store_dwordx4 v23, v[80:83], s[86:87] nt
	s_waitcnt vmcnt(7)
	global_store_dwordx4 v23, v[84:87], s[86:87] offset:1024 nt
	s_waitcnt vmcnt(7)
	global_store_dwordx4 v23, v[88:91], s[86:87] offset:2048 nt
	s_waitcnt vmcnt(7)
	global_store_dwordx4 v23, v[92:95], s[86:87] offset:3072 nt
